# ret_out: Q/K/V/rotary-table loads batched (flat->global, counted vmcnt); EpiGate z0 variant
# speedup vs baseline: 1.0182x; 1.0182x over previous
.LBB0_79:
	s_ashr_i32 s8, s58, 7
	s_ashr_i32 s9, s8, 31
	s_lshl_b64 s[42:43], s[8:9], 12
	s_and_b32 s8, s13, 0xf80
	s_or_b32 s42, s42, s8
	v_lshl_add_u64 v[4:5], s[42:43], 0, v[68:69]
	v_mov_b64_e32 v[6:7], s[26:27]
	v_add_u32_e32 v2, s8, v68
	v_mad_u64_u32 v[18:19], s[8:9], v4, s83, v[6:7]
	v_mad_i32_i24 v19, v5, s83, v19
	s_lshl_b32 s36, s15, 8
	v_ashrrev_i32_e32 v3, 31, v2
	v_lshl_add_u64 v[4:5], v[18:19], 0, s[36:37]
	v_lshl_add_u64 v[22:23], v[4:5], 0, v[0:1]
	v_lshlrev_b64 v[2:3], 9, v[2:3]
	global_load_dwordx4 v[10:13], v[22:23], off offset:128
	global_load_dwordx4 v[14:17], v[22:23], off
	v_lshl_add_u64 v[20:21], v[70:71], 0, v[2:3]
	global_load_dwordx4 v[26:29], v[20:21], off
	v_mul_f32_e32 v2, v24, v67
	s_mov_b32 s8, 0xc2fc0000
	v_cmp_gt_f32_e32 vcc, s8, v2
	s_mov_b32 s9, s37
	v_mov_b32_e32 v95, v1
	v_cndmask_b32_e32 v2, 0, v201, vcc
	v_fmac_f32_e32 v2, v24, v67
	v_exp_f32_e32 v2, v2
	v_cndmask_b32_e32 v3, 0, v200, vcc
	v_readlane_b32 s4, v250, 43
	v_readlane_b32 s5, v250, 44
	v_ldexp_f32 v25, v2, v3
	global_load_dwordx4 v[2:5], v[22:23], off offset:16
	global_load_dwordx4 v[6:9], v[22:23], off offset:144
	global_load_dwordx4 v[38:41], v[20:21], off offset:16
	global_load_dwordx4 v[42:45], v[20:21], off offset:32
	global_load_dwordx4 v[46:49], v[20:21], off offset:48
	global_load_dwordx4 v[50:53], v[20:21], off offset:64
	global_load_dwordx4 v[54:57], v[20:21], off offset:80
	global_load_dwordx4 v[62:65], v[20:21], off offset:96
	global_load_dwordx4 v[98:101], v[20:21], off offset:112
	v_lshl_add_u64 v[58:59], v[92:93], 0, v[72:73]
	s_waitcnt vmcnt(9)
	v_lshlrev_b32_e32 v31, 16, v10
	v_lshlrev_b32_e32 v30, 16, v14
	v_and_b32_e32 v33, 0xffff0000, v10
	v_and_b32_e32 v32, 0xffff0000, v14
	v_pk_mul_f32 v[34:35], v[26:27], v[30:31]
	v_pk_mul_f32 v[36:37], v[28:29], v[32:33]
	v_pk_mul_f32 v[26:27], v[26:27], v[30:31] op_sel:[1,0] op_sel_hi:[0,1]
	v_pk_mul_f32 v[28:29], v[28:29], v[32:33] op_sel:[1,0] op_sel_hi:[0,1]
	v_sub_f32_e32 v10, v34, v35
	v_sub_f32_e32 v14, v36, v37
	v_add_f32_e32 v26, v26, v27
	v_add_f32_e32 v27, v28, v29
	v_mul_f32_e32 v10, v25, v10
	v_mul_f32_e32 v14, v25, v14
	v_mul_f32_e32 v26, v25, v26
	v_mul_f32_e32 v27, v25, v27
	v_cvt_pk_bf16_f32 v14, v10, v14
	v_cvt_pk_bf16_f32 v10, v26, v27
	v_lshlrev_b32_e32 v31, 16, v11
	v_lshlrev_b32_e32 v30, 16, v15
	v_and_b32_e32 v33, 0xffff0000, v11
	v_and_b32_e32 v32, 0xffff0000, v15
	s_waitcnt vmcnt(6)
	v_pk_mul_f32 v[34:35], v[38:39], v[30:31]
	v_pk_mul_f32 v[36:37], v[40:41], v[32:33]
	v_pk_mul_f32 v[38:39], v[38:39], v[30:31] op_sel:[1,0] op_sel_hi:[0,1]
	v_pk_mul_f32 v[40:41], v[40:41], v[32:33] op_sel:[1,0] op_sel_hi:[0,1]
	v_sub_f32_e32 v11, v34, v35
	v_sub_f32_e32 v15, v36, v37
	v_add_f32_e32 v38, v38, v39
	v_add_f32_e32 v39, v40, v41
	v_mul_f32_e32 v11, v25, v11
	v_mul_f32_e32 v15, v25, v15
	v_mul_f32_e32 v38, v25, v38
	v_mul_f32_e32 v39, v25, v39
	v_cvt_pk_bf16_f32 v15, v11, v15
	v_cvt_pk_bf16_f32 v11, v38, v39
	v_lshlrev_b32_e32 v31, 16, v12
	v_lshlrev_b32_e32 v30, 16, v16
	v_and_b32_e32 v33, 0xffff0000, v12
	v_and_b32_e32 v32, 0xffff0000, v16
	s_waitcnt vmcnt(5)
	v_pk_mul_f32 v[34:35], v[42:43], v[30:31]
	v_pk_mul_f32 v[36:37], v[44:45], v[32:33]
	v_pk_mul_f32 v[42:43], v[42:43], v[30:31] op_sel:[1,0] op_sel_hi:[0,1]
	v_pk_mul_f32 v[44:45], v[44:45], v[32:33] op_sel:[1,0] op_sel_hi:[0,1]
	v_sub_f32_e32 v12, v34, v35
	v_sub_f32_e32 v16, v36, v37
	v_add_f32_e32 v42, v42, v43
	v_add_f32_e32 v43, v44, v45
	v_mul_f32_e32 v12, v25, v12
	v_mul_f32_e32 v16, v25, v16
	v_mul_f32_e32 v42, v25, v42
	v_mul_f32_e32 v43, v25, v43
	v_cvt_pk_bf16_f32 v16, v12, v16
	v_cvt_pk_bf16_f32 v12, v42, v43
	v_lshlrev_b32_e32 v31, 16, v13
	v_lshlrev_b32_e32 v30, 16, v17
	v_and_b32_e32 v33, 0xffff0000, v13
	v_and_b32_e32 v32, 0xffff0000, v17
	s_waitcnt vmcnt(4)
	v_pk_mul_f32 v[34:35], v[46:47], v[30:31]
	v_pk_mul_f32 v[36:37], v[48:49], v[32:33]
	v_pk_mul_f32 v[46:47], v[46:47], v[30:31] op_sel:[1,0] op_sel_hi:[0,1]
	v_pk_mul_f32 v[48:49], v[48:49], v[32:33] op_sel:[1,0] op_sel_hi:[0,1]
	v_sub_f32_e32 v13, v34, v35
	v_sub_f32_e32 v17, v36, v37
	v_add_f32_e32 v46, v46, v47
	v_add_f32_e32 v47, v48, v49
	v_mul_f32_e32 v13, v25, v13
	v_mul_f32_e32 v17, v25, v17
	v_mul_f32_e32 v46, v25, v46
	v_mul_f32_e32 v47, v25, v47
	v_cvt_pk_bf16_f32 v17, v13, v17
	v_cvt_pk_bf16_f32 v13, v46, v47
	v_lshlrev_b32_e32 v31, 16, v6
	v_lshlrev_b32_e32 v30, 16, v2
	v_and_b32_e32 v33, 0xffff0000, v6
	v_and_b32_e32 v32, 0xffff0000, v2
	s_waitcnt vmcnt(3)
	v_pk_mul_f32 v[34:35], v[50:51], v[30:31]
	v_pk_mul_f32 v[36:37], v[52:53], v[32:33]
	v_pk_mul_f32 v[50:51], v[50:51], v[30:31] op_sel:[1,0] op_sel_hi:[0,1]
	v_pk_mul_f32 v[52:53], v[52:53], v[32:33] op_sel:[1,0] op_sel_hi:[0,1]
	v_sub_f32_e32 v2, v34, v35
	v_sub_f32_e32 v6, v36, v37
	v_add_f32_e32 v50, v50, v51
	v_add_f32_e32 v51, v52, v53
	v_mul_f32_e32 v2, v25, v2
	v_mul_f32_e32 v6, v25, v6
	v_mul_f32_e32 v50, v25, v50
	v_mul_f32_e32 v51, v25, v51
	v_cvt_pk_bf16_f32 v2, v2, v6
	v_cvt_pk_bf16_f32 v6, v50, v51
	v_lshlrev_b32_e32 v31, 16, v7
	v_lshlrev_b32_e32 v30, 16, v3
	v_and_b32_e32 v33, 0xffff0000, v7
	v_and_b32_e32 v32, 0xffff0000, v3
	s_waitcnt vmcnt(2)
	v_pk_mul_f32 v[34:35], v[54:55], v[30:31]
	v_pk_mul_f32 v[36:37], v[56:57], v[32:33]
	v_pk_mul_f32 v[54:55], v[54:55], v[30:31] op_sel:[1,0] op_sel_hi:[0,1]
	v_pk_mul_f32 v[56:57], v[56:57], v[32:33] op_sel:[1,0] op_sel_hi:[0,1]
	v_sub_f32_e32 v3, v34, v35
	v_sub_f32_e32 v7, v36, v37
	v_add_f32_e32 v54, v54, v55
	v_add_f32_e32 v55, v56, v57
	v_mul_f32_e32 v3, v25, v3
	v_mul_f32_e32 v7, v25, v7
	v_mul_f32_e32 v54, v25, v54
	v_mul_f32_e32 v55, v25, v55
	v_cvt_pk_bf16_f32 v3, v3, v7
	v_cvt_pk_bf16_f32 v7, v54, v55
	v_lshlrev_b32_e32 v31, 16, v8
	v_lshlrev_b32_e32 v30, 16, v4
	v_and_b32_e32 v33, 0xffff0000, v8
	v_and_b32_e32 v32, 0xffff0000, v4
	s_waitcnt vmcnt(1)
	v_pk_mul_f32 v[34:35], v[62:63], v[30:31]
	v_pk_mul_f32 v[36:37], v[64:65], v[32:33]
	v_pk_mul_f32 v[62:63], v[62:63], v[30:31] op_sel:[1,0] op_sel_hi:[0,1]
	v_pk_mul_f32 v[64:65], v[64:65], v[32:33] op_sel:[1,0] op_sel_hi:[0,1]
	v_sub_f32_e32 v4, v34, v35
	v_sub_f32_e32 v8, v36, v37
	v_add_f32_e32 v62, v62, v63
	v_add_f32_e32 v63, v64, v65
	v_mul_f32_e32 v4, v25, v4
	v_mul_f32_e32 v8, v25, v8
	v_mul_f32_e32 v62, v25, v62
	v_mul_f32_e32 v63, v25, v63
	v_cvt_pk_bf16_f32 v4, v4, v8
	v_cvt_pk_bf16_f32 v8, v62, v63
	v_lshlrev_b32_e32 v31, 16, v9
	v_lshlrev_b32_e32 v30, 16, v5
	v_and_b32_e32 v33, 0xffff0000, v9
	v_and_b32_e32 v32, 0xffff0000, v5
	s_waitcnt vmcnt(0)
	v_pk_mul_f32 v[34:35], v[98:99], v[30:31]
	v_pk_mul_f32 v[36:37], v[100:101], v[32:33]
	v_pk_mul_f32 v[98:99], v[98:99], v[30:31] op_sel:[1,0] op_sel_hi:[0,1]
	v_pk_mul_f32 v[100:101], v[100:101], v[32:33] op_sel:[1,0] op_sel_hi:[0,1]
	v_sub_f32_e32 v5, v34, v35
	v_sub_f32_e32 v9, v36, v37
	v_add_f32_e32 v98, v98, v99
	v_add_f32_e32 v99, v100, v101
	v_mul_f32_e32 v5, v25, v5
	v_mul_f32_e32 v9, v25, v9
	v_mul_f32_e32 v98, v25, v98
	v_mul_f32_e32 v25, v25, v99
	v_cvt_pk_bf16_f32 v5, v5, v9
	v_cvt_pk_bf16_f32 v9, v98, v25
	ds_write_b128 v75, v[14:17]
	ds_write_b128 v75, v[10:13] offset:128
	ds_write_b128 v75, v[2:5] offset:16
	ds_write_b128 v75, v[6:9] offset:144
	global_load_dwordx4 v[10:13], v[20:21], off
	global_load_dwordx4 v[14:17], v[22:23], off offset:1152
	global_load_dwordx4 v[26:29], v[22:23], off offset:1024
	v_mul_f32_e64 v2, v24, -v67
	v_cmp_gt_f32_e32 vcc, s8, v2
	s_lshl_b32 s8, s15, 9
	v_lshl_add_u64 v[18:19], v[18:19], 0, s[8:9]
	v_cndmask_b32_e32 v2, 0, v201, vcc
	v_fma_f32 v2, v24, -v67, v2
	v_exp_f32_e32 v2, v2
	v_cndmask_b32_e32 v3, 0, v200, vcc
	v_lshl_add_u64 v[18:19], v[18:19], 0, v[94:95]
	s_mov_b32 s8, 0x19380000
	v_ldexp_f32 v24, v2, v3
	global_load_dwordx4 v[2:5], v[22:23], off offset:1040
	global_load_dwordx4 v[6:9], v[22:23], off offset:1168
	global_load_dwordx4 v[116:119], v[20:21], off offset:16
	global_load_dwordx4 v[120:123], v[20:21], off offset:32
	global_load_dwordx4 v[124:127], v[20:21], off offset:48
	global_load_dwordx4 v[128:131], v[20:21], off offset:64
	global_load_dwordx4 v[132:135], v[20:21], off offset:80
	global_load_dwordx4 v[136:139], v[20:21], off offset:96
	global_load_dwordx4 v[140:143], v[20:21], off offset:112
	global_load_dwordx4 v[144:147], v[18:19], off offset:2048
	global_load_dwordx4 v[148:151], v[18:19], off offset:2064
	global_load_dwordx4 v[152:155], v[18:19], off offset:2080
	global_load_dwordx4 v[182:185], v[18:19], off offset:2096
	global_load_dwordx4 v[186:189], v[18:19], off offset:2112
	global_load_dwordx4 v[190:193], v[18:19], off offset:2128
	global_load_dwordx4 v[210:213], v[18:19], off offset:2144
	global_load_dwordx4 v[214:217], v[18:19], off offset:2160
	v_add_co_u32_e32 v60, vcc, s8, v58
	v_xor_b32_e32 v95, 16, v195
	s_nop 0
	v_addc_co_u32_e32 v61, vcc, 0, v59, vcc
	v_lshl_add_u64 v[58:59], v[90:91], 0, v[72:73]
	v_add_co_u32_e32 v58, vcc, s8, v58
	s_waitcnt vmcnt(17)
	v_mov_b32_e32 v25, v10
	v_and_b32_e32 v23, 0xffff0000, v14
	v_and_b32_e32 v22, 0xffff0000, v26
	v_lshlrev_b32_e32 v31, 16, v26
	v_lshlrev_b32_e32 v30, 16, v14
	v_pk_mul_f32 v[32:33], v[12:13], v[22:23]
	v_mov_b32_e32 v159, v31
	v_pk_mul_f32 v[34:35], v[10:11], v[30:31]
	v_pk_mul_f32 v[12:13], v[12:13], v[22:23] op_sel:[1,0] op_sel_hi:[0,1]
	v_pk_mul_f32 v[22:23], v[24:25], v[158:159]
	v_sub_f32_e32 v10, v32, v33
	v_add_f32_e32 v14, v35, v34
	v_add_f32_e32 v12, v12, v13
	v_fma_f32 v11, -v11, v30, v23
	v_mul_f32_e32 v10, v22, v10
	v_mul_f32_e32 v13, v22, v14
	v_mul_f32_e32 v12, v22, v12
	v_mul_f32_e32 v11, v22, v11
	v_cvt_pk_bf16_f32 v10, v11, v10
	v_cvt_pk_bf16_f32 v14, v13, v12
	v_lshlrev_b32_e32 v13, 16, v15
	v_lshlrev_b32_e32 v12, 16, v27
	v_and_b32_e32 v25, 0xffff0000, v15
	v_and_b32_e32 v24, 0xffff0000, v27
	v_addc_co_u32_e32 v59, vcc, 0, v59, vcc
	s_waitcnt vmcnt(14)
	v_pk_mul_f32 v[26:27], v[116:117], v[12:13]
	v_pk_mul_f32 v[34:35], v[118:119], v[24:25]
	v_pk_mul_f32 v[12:13], v[116:117], v[12:13] op_sel:[1,0] op_sel_hi:[0,1]
	v_pk_mul_f32 v[24:25], v[118:119], v[24:25] op_sel:[1,0] op_sel_hi:[0,1]
	v_sub_f32_e32 v11, v26, v27
	v_sub_f32_e32 v15, v34, v35
	v_add_f32_e32 v12, v12, v13
	v_add_f32_e32 v13, v24, v25
	v_mul_f32_e32 v11, v22, v11
	v_mul_f32_e32 v15, v22, v15
	v_mul_f32_e32 v12, v22, v12
	v_mul_f32_e32 v13, v22, v13
	v_cvt_pk_bf16_f32 v11, v11, v15
	v_cvt_pk_bf16_f32 v15, v12, v13
	v_lshlrev_b32_e32 v13, 16, v16
	v_lshlrev_b32_e32 v12, 16, v28
	v_and_b32_e32 v31, 0xffff0000, v16
	v_and_b32_e32 v30, 0xffff0000, v28
	s_waitcnt vmcnt(13)
	v_pk_mul_f32 v[32:33], v[120:121], v[12:13]
	v_pk_mul_f32 v[12:13], v[120:121], v[12:13] op_sel:[1,0] op_sel_hi:[0,1]
	v_pk_mul_f32 v[34:35], v[122:123], v[30:31]
	v_pk_mul_f32 v[120:121], v[122:123], v[30:31] op_sel:[1,0] op_sel_hi:[0,1]
	v_sub_f32_e32 v16, v32, v33
	v_add_f32_e32 v12, v12, v13
	v_sub_f32_e32 v23, v34, v35
	v_add_f32_e32 v13, v120, v121
	v_mul_f32_e32 v16, v22, v16
	v_mul_f32_e32 v120, v22, v12
	v_mul_f32_e32 v23, v22, v23
	v_mul_f32_e32 v13, v22, v13
	v_cvt_pk_bf16_f32 v12, v16, v23
	v_cvt_pk_bf16_f32 v16, v120, v13
	v_lshlrev_b32_e32 v31, 16, v17
	v_lshlrev_b32_e32 v30, 16, v29
	v_and_b32_e32 v33, 0xffff0000, v17
	v_and_b32_e32 v32, 0xffff0000, v29
	s_waitcnt vmcnt(12)
	v_pk_mul_f32 v[28:29], v[124:125], v[30:31]
	v_pk_mul_f32 v[34:35], v[126:127], v[32:33]
	v_pk_mul_f32 v[124:125], v[124:125], v[30:31] op_sel:[1,0] op_sel_hi:[0,1]
	v_pk_mul_f32 v[126:127], v[126:127], v[32:33] op_sel:[1,0] op_sel_hi:[0,1]
	v_sub_f32_e32 v13, v28, v29
	v_sub_f32_e32 v17, v34, v35
	v_add_f32_e32 v23, v124, v125
	v_add_f32_e32 v124, v126, v127
	v_mul_f32_e32 v13, v22, v13
	v_mul_f32_e32 v17, v22, v17
	v_mul_f32_e32 v124, v22, v124
	v_mul_f32_e32 v23, v22, v23
	v_cvt_pk_bf16_f32 v13, v13, v17
	v_cvt_pk_bf16_f32 v17, v23, v124
	v_lshlrev_b32_e32 v29, 16, v6
	v_lshlrev_b32_e32 v28, 16, v2
	v_and_b32_e32 v31, 0xffff0000, v6
	v_and_b32_e32 v30, 0xffff0000, v2
	s_waitcnt vmcnt(11)
	v_pk_mul_f32 v[32:33], v[128:129], v[28:29]
	v_pk_mul_f32 v[34:35], v[130:131], v[30:31]
	v_pk_mul_f32 v[128:129], v[128:129], v[28:29] op_sel:[1,0] op_sel_hi:[0,1]
	v_pk_mul_f32 v[130:131], v[130:131], v[30:31] op_sel:[1,0] op_sel_hi:[0,1]
	v_sub_f32_e32 v2, v32, v33
	v_sub_f32_e32 v6, v34, v35
	v_add_f32_e32 v23, v128, v129
	v_add_f32_e32 v128, v130, v131
	v_mul_f32_e32 v2, v22, v2
	v_mul_f32_e32 v6, v22, v6
	v_mul_f32_e32 v128, v22, v128
	v_mul_f32_e32 v23, v22, v23
	v_cvt_pk_bf16_f32 v2, v2, v6
	v_cvt_pk_bf16_f32 v6, v23, v128
	v_lshlrev_b32_e32 v29, 16, v7
	v_lshlrev_b32_e32 v28, 16, v3
	v_and_b32_e32 v31, 0xffff0000, v7
	v_and_b32_e32 v30, 0xffff0000, v3
	s_waitcnt vmcnt(10)
	v_pk_mul_f32 v[32:33], v[132:133], v[28:29]
	v_pk_mul_f32 v[34:35], v[134:135], v[30:31]
	v_pk_mul_f32 v[132:133], v[132:133], v[28:29] op_sel:[1,0] op_sel_hi:[0,1]
	v_pk_mul_f32 v[134:135], v[134:135], v[30:31] op_sel:[1,0] op_sel_hi:[0,1]
	v_sub_f32_e32 v3, v32, v33
	v_sub_f32_e32 v7, v34, v35
	v_add_f32_e32 v23, v132, v133
	v_add_f32_e32 v132, v134, v135
	v_mul_f32_e32 v3, v22, v3
	v_mul_f32_e32 v7, v22, v7
	v_mul_f32_e32 v132, v22, v132
	v_mul_f32_e32 v23, v22, v23
	v_cvt_pk_bf16_f32 v3, v3, v7
	v_cvt_pk_bf16_f32 v7, v23, v132
	v_lshlrev_b32_e32 v29, 16, v8
	v_lshlrev_b32_e32 v28, 16, v4
	v_and_b32_e32 v31, 0xffff0000, v8
	v_and_b32_e32 v30, 0xffff0000, v4
	s_waitcnt vmcnt(9)
	v_pk_mul_f32 v[32:33], v[136:137], v[28:29]
	v_pk_mul_f32 v[34:35], v[138:139], v[30:31]
	v_pk_mul_f32 v[136:137], v[136:137], v[28:29] op_sel:[1,0] op_sel_hi:[0,1]
	v_pk_mul_f32 v[138:139], v[138:139], v[30:31] op_sel:[1,0] op_sel_hi:[0,1]
	v_sub_f32_e32 v4, v32, v33
	v_sub_f32_e32 v8, v34, v35
	v_add_f32_e32 v23, v136, v137
	v_add_f32_e32 v136, v138, v139
	v_mul_f32_e32 v4, v22, v4
	v_mul_f32_e32 v8, v22, v8
	v_mul_f32_e32 v136, v22, v136
	v_mul_f32_e32 v23, v22, v23
	v_cvt_pk_bf16_f32 v4, v4, v8
	v_cvt_pk_bf16_f32 v8, v23, v136
	v_lshlrev_b32_e32 v21, 16, v9
	v_lshlrev_b32_e32 v20, 16, v5
	v_and_b32_e32 v29, 0xffff0000, v9
	v_and_b32_e32 v28, 0xffff0000, v5
	s_waitcnt vmcnt(8)
	v_pk_mul_f32 v[30:31], v[140:141], v[20:21]
	v_pk_mul_f32 v[32:33], v[142:143], v[28:29]
	v_pk_mul_f32 v[20:21], v[140:141], v[20:21] op_sel:[1,0] op_sel_hi:[0,1]
	v_pk_mul_f32 v[140:141], v[142:143], v[28:29] op_sel:[1,0] op_sel_hi:[0,1]
	v_sub_f32_e32 v5, v30, v31
	v_sub_f32_e32 v9, v32, v33
	v_add_f32_e32 v20, v20, v21
	v_add_f32_e32 v21, v140, v141
	v_mul_f32_e32 v5, v22, v5
	v_mul_f32_e32 v9, v22, v9
	v_mul_f32_e32 v20, v22, v20
	v_mul_f32_e32 v21, v22, v21
	v_cvt_pk_bf16_f32 v5, v5, v9
	v_cvt_pk_bf16_f32 v9, v20, v21
	ds_write_b128 v75, v[10:13] offset:34816
	ds_write_b128 v75, v[14:17] offset:34944
	ds_write_b128 v75, v[2:5] offset:34832
	ds_write_b128 v75, v[6:9] offset:34960
	s_waitcnt vmcnt(7)
	ds_write_b16 v77, v144
	ds_write_b16_d16_hi v77, v144 offset:272
	ds_write_b16 v77, v145 offset:544
	ds_write_b16_d16_hi v77, v145 offset:816
	ds_write_b16 v77, v146 offset:1088
	ds_write_b16_d16_hi v77, v146 offset:1360
	ds_write_b16 v77, v147 offset:1632
	ds_write_b16_d16_hi v77, v147 offset:1904
	s_waitcnt vmcnt(6)
	ds_write_b16 v77, v148 offset:2176
	ds_write_b16_d16_hi v77, v148 offset:2448
	ds_write_b16 v77, v149 offset:2720
	ds_write_b16_d16_hi v77, v149 offset:2992
	ds_write_b16 v77, v150 offset:3264
	ds_write_b16_d16_hi v77, v150 offset:3536
	ds_write_b16 v77, v151 offset:3808
	ds_write_b16_d16_hi v77, v151 offset:4080
	s_waitcnt vmcnt(5)
	ds_write_b16 v77, v152 offset:4352
	ds_write_b16_d16_hi v77, v152 offset:4624
	ds_write_b16 v77, v153 offset:4896
	ds_write_b16_d16_hi v77, v153 offset:5168
	ds_write_b16 v77, v154 offset:5440
	ds_write_b16_d16_hi v77, v154 offset:5712
	ds_write_b16 v77, v155 offset:5984
	ds_write_b16_d16_hi v77, v155 offset:6256
	s_waitcnt vmcnt(4)
	ds_write_b16 v77, v182 offset:6528
	ds_write_b16_d16_hi v77, v182 offset:6800
	ds_write_b16 v77, v183 offset:7072
	ds_write_b16_d16_hi v77, v183 offset:7344
	ds_write_b16 v77, v184 offset:7616
	ds_write_b16_d16_hi v77, v184 offset:7888
	ds_write_b16 v77, v185 offset:8160
	ds_write_b16_d16_hi v77, v185 offset:8432
	s_waitcnt vmcnt(3)
	ds_write_b16 v77, v186 offset:8704
	ds_write_b16_d16_hi v77, v186 offset:8976
	ds_write_b16 v77, v187 offset:9248
	ds_write_b16_d16_hi v77, v187 offset:9520
	ds_write_b16 v77, v188 offset:9792
	ds_write_b16_d16_hi v77, v188 offset:10064
	ds_write_b16 v77, v189 offset:10336
	ds_write_b16_d16_hi v77, v189 offset:10608
	s_waitcnt vmcnt(2)
	ds_write_b16 v77, v190 offset:10880
	ds_write_b16_d16_hi v77, v190 offset:11152
	ds_write_b16 v77, v191 offset:11424
	ds_write_b16_d16_hi v77, v191 offset:11696
	ds_write_b16 v77, v192 offset:11968
	ds_write_b16_d16_hi v77, v192 offset:12240
	ds_write_b16 v77, v193 offset:12512
	ds_write_b16_d16_hi v77, v193 offset:12784
	s_waitcnt vmcnt(1)
	ds_write_b16 v77, v210 offset:13056
	ds_write_b16_d16_hi v77, v210 offset:13328
	ds_write_b16 v77, v211 offset:13600
	ds_write_b16_d16_hi v77, v211 offset:13872
	ds_write_b16 v77, v212 offset:14144
	ds_write_b16_d16_hi v77, v212 offset:14416
	ds_write_b16 v77, v213 offset:14688
	ds_write_b16_d16_hi v77, v213 offset:14960
	s_waitcnt vmcnt(0)
	ds_write_b16 v77, v214 offset:15232
	ds_write_b16_d16_hi v77, v214 offset:15504
	ds_write_b16 v77, v215 offset:15776
	ds_write_b16_d16_hi v77, v215 offset:16048
	ds_write_b16 v77, v216 offset:16320
	ds_write_b16_d16_hi v77, v216 offset:16592
	ds_write_b16 v77, v217 offset:16864
	ds_write_b16_d16_hi v77, v217 offset:17136
	s_waitcnt lgkmcnt(0)
	s_barrier
	ds_read_b128 v[2:5], v112 offset:34816
	ds_read_b128 v[6:9], v79
	ds_read_b128 v[10:13], v112 offset:39168
	ds_read_b128 v[14:17], v112 offset:43520
	ds_read_b128 v[18:21], v112 offset:47872
	ds_read_b128 v[22:25], v112 offset:52224
	ds_read_b128 v[26:29], v112 offset:56576
	ds_read_b128 v[30:33], v112 offset:60928
	ds_read_b128 v[34:37], v112 offset:65280
	s_waitcnt lgkmcnt(7)
	v_mfma_f32_16x16x32_bf16 v[2:5], v[2:5], v[6:9], 0
	ds_read_b128 v[38:41], v112 offset:34880
	ds_read_b128 v[42:45], v79 offset:64
	s_waitcnt lgkmcnt(8)
	v_mfma_f32_16x16x32_bf16 v[10:13], v[10:13], v[6:9], 0
	s_waitcnt lgkmcnt(7)
	v_mfma_f32_16x16x32_bf16 v[14:17], v[14:17], v[6:9], 0
	s_waitcnt lgkmcnt(6)
	v_mfma_f32_16x16x32_bf16 v[18:21], v[18:21], v[6:9], 0
	s_waitcnt lgkmcnt(5)
	v_mfma_f32_16x16x32_bf16 v[22:25], v[22:25], v[6:9], 0
	s_waitcnt lgkmcnt(4)
	v_mfma_f32_16x16x32_bf16 v[26:29], v[26:29], v[6:9], 0
	s_waitcnt lgkmcnt(3)
	v_mfma_f32_16x16x32_bf16 v[30:33], v[30:33], v[6:9], 0
	s_waitcnt lgkmcnt(2)
	v_mfma_f32_16x16x32_bf16 v[6:9], v[34:37], v[6:9], 0
	ds_read_b128 v[34:37], v112 offset:39232
	s_waitcnt lgkmcnt(1)
	v_mfma_f32_16x16x32_bf16 v[2:5], v[38:41], v[42:45], v[2:5]
	ds_read_b128 v[38:41], v112 offset:43584
	s_waitcnt lgkmcnt(1)
	v_mfma_f32_16x16x32_bf16 v[10:13], v[34:37], v[42:45], v[10:13]
	ds_read_b128 v[34:37], v112 offset:47936
	s_waitcnt lgkmcnt(1)
	v_mfma_f32_16x16x32_bf16 v[14:17], v[38:41], v[42:45], v[14:17]
	ds_read_b128 v[38:41], v112 offset:52288
	s_waitcnt lgkmcnt(1)
	v_mfma_f32_16x16x32_bf16 v[18:21], v[34:37], v[42:45], v[18:21]
	ds_read_b128 v[34:37], v112 offset:56640
	s_waitcnt lgkmcnt(1)
	v_mfma_f32_16x16x32_bf16 v[22:25], v[38:41], v[42:45], v[22:25]
	ds_read_b128 v[38:41], v112 offset:60992
	s_waitcnt lgkmcnt(1)
	v_mfma_f32_16x16x32_bf16 v[26:29], v[34:37], v[42:45], v[26:29]
	ds_read_b128 v[34:37], v112 offset:65344
	s_waitcnt lgkmcnt(1)
	v_mfma_f32_16x16x32_bf16 v[30:33], v[38:41], v[42:45], v[30:33]
	ds_read_b128 v[38:41], v112 offset:34944
	ds_read_b128 v[46:49], v79 offset:128
	s_waitcnt lgkmcnt(2)
	v_mfma_f32_16x16x32_bf16 v[6:9], v[34:37], v[42:45], v[6:9]
	ds_read_b128 v[34:37], v112 offset:39296
	v_add_u32_e32 v42, 0x8800, v113
	s_waitcnt lgkmcnt(1)
	v_mfma_f32_16x16x32_bf16 v[2:5], v[38:41], v[46:49], v[2:5]
	ds_read_b128 v[38:41], v112 offset:43648
	s_waitcnt lgkmcnt(1)
	v_mfma_f32_16x16x32_bf16 v[10:13], v[34:37], v[46:49], v[10:13]
	ds_read_b128 v[34:37], v112 offset:48000
	s_waitcnt lgkmcnt(1)
	v_mfma_f32_16x16x32_bf16 v[14:17], v[38:41], v[46:49], v[14:17]
	ds_read_b128 v[38:41], v112 offset:52352
	s_waitcnt lgkmcnt(1)
	v_mfma_f32_16x16x32_bf16 v[18:21], v[34:37], v[46:49], v[18:21]
	ds_read_b128 v[34:37], v112 offset:56704
	s_waitcnt lgkmcnt(1)
	v_mfma_f32_16x16x32_bf16 v[22:25], v[38:41], v[46:49], v[22:25]
	ds_read_b128 v[38:41], v112 offset:61056
	s_waitcnt lgkmcnt(1)
	v_mfma_f32_16x16x32_bf16 v[26:29], v[34:37], v[46:49], v[26:29]
	ds_read_b128 v[34:37], v112 offset:65408
	s_waitcnt lgkmcnt(1)
	v_mfma_f32_16x16x32_bf16 v[30:33], v[38:41], v[46:49], v[30:33]
	ds_read_b128 v[38:41], v112 offset:35008
	s_waitcnt lgkmcnt(1)
	v_mfma_f32_16x16x32_bf16 v[6:9], v[34:37], v[46:49], v[6:9]
	ds_read_b128 v[34:37], v79 offset:192
	s_waitcnt lgkmcnt(0)
	v_mfma_f32_16x16x32_bf16 v[2:5], v[38:41], v[34:37], v[2:5]
	ds_read_b128 v[38:41], v112 offset:39360
	s_waitcnt lgkmcnt(0)
	v_mfma_f32_16x16x32_bf16 v[10:13], v[38:41], v[34:37], v[10:13]
	ds_read_b128 v[38:41], v112 offset:43712
	s_nop 3
	v_cndmask_b32_e64 v2, v2, 0, s[18:19]
	v_cndmask_b32_e64 v3, 0, v3, s[22:23]
	s_waitcnt lgkmcnt(0)
	v_mfma_f32_16x16x32_bf16 v[14:17], v[38:41], v[34:37], v[14:17]
	ds_read_b128 v[38:41], v112 offset:48064
	v_cndmask_b32_e64 v4, v4, 0, s[72:73]
	v_cndmask_b32_e64 v5, v5, 0, s[60:61]
	s_waitcnt lgkmcnt(0)
	v_mfma_f32_16x16x32_bf16 v[18:21], v[38:41], v[34:37], v[18:21]
	ds_read_b128 v[38:41], v112 offset:52416
	v_cndmask_b32_e64 v10, v10, 0, s[62:63]
	v_cndmask_b32_e64 v11, v11, 0, s[64:65]
	s_waitcnt lgkmcnt(0)
	v_mfma_f32_16x16x32_bf16 v[22:25], v[38:41], v[34:37], v[22:25]
	ds_read_b128 v[38:41], v112 offset:56768
	v_cndmask_b32_e64 v12, v12, 0, s[66:67]
	v_cndmask_b32_e64 v13, v13, 0, s[68:69]
	s_waitcnt lgkmcnt(0)
	v_mfma_f32_16x16x32_bf16 v[26:29], v[38:41], v[34:37], v[26:29]
	ds_read_b128 v[38:41], v112 offset:61120
	v_cndmask_b32_e64 v14, v14, 0, s[70:71]
	v_cndmask_b32_e64 v15, v15, 0, s[44:45]
	s_waitcnt lgkmcnt(0)
	v_mfma_f32_16x16x32_bf16 v[30:33], v[38:41], v[34:37], v[30:33]
	ds_read_b128 v[38:41], v112 offset:65472
	v_cndmask_b32_e64 v16, v16, 0, s[74:75]
	v_cndmask_b32_e64 v17, v17, 0, s[76:77]
	s_waitcnt lgkmcnt(0)
	v_mfma_f32_16x16x32_bf16 v[6:9], v[38:41], v[34:37], v[6:9]
	v_cndmask_b32_e64 v18, v18, 0, s[78:79]
	v_cndmask_b32_e64 v19, v19, 0, s[46:47]
	v_cndmask_b32_e64 v20, v20, 0, s[48:49]
	s_nop 4
	v_cndmask_b32_e64 v35, v7, 0, s[4:5]
	v_readlane_b32 s4, v250, 45
	v_readlane_b32 s5, v250, 46
	v_cndmask_b32_e64 v21, v21, 0, s[50:51]
	v_cndmask_b32_e64 v34, v6, 0, s[20:21]
	v_cndmask_b32_e64 v36, v8, 0, s[4:5]
	v_readlane_b32 s4, v250, 47
	v_readlane_b32 s5, v250, 48
	v_cvt_pk_bf16_f32 v2, v2, v3
	v_cvt_pk_bf16_f32 v3, v4, v5
	v_cvt_pk_bf16_f32 v4, v10, v11
	v_cvt_pk_bf16_f32 v5, v12, v13
	v_cvt_pk_bf16_f32 v6, v14, v15
	s_nop 1
	v_cndmask_b32_e64 v37, v9, 0, s[4:5]
	v_cvt_pk_bf16_f32 v7, v16, v17
	v_cvt_pk_bf16_f32 v8, v18, v19
	v_cvt_pk_bf16_f32 v9, v20, v21
	v_cndmask_b32_e64 v22, v22, 0, s[52:53]
	v_cndmask_b32_e64 v23, v23, 0, s[54:55]
	v_cndmask_b32_e64 v24, v24, 0, s[56:57]
	v_cndmask_b32_e64 v25, v25, 0, s[92:93]
	v_cndmask_b32_e64 v26, v26, 0, s[94:95]
	v_cndmask_b32_e64 v27, v27, 0, s[38:39]
	v_cndmask_b32_e64 v28, v28, 0, s[96:97]
	v_cndmask_b32_e64 v29, v29, 0, s[0:1]
	v_cndmask_b32_e64 v30, v30, 0, s[2:3]
	v_cndmask_b32_e64 v31, v31, 0, s[24:25]
	v_cndmask_b32_e64 v32, v32, 0, s[28:29]
	v_cndmask_b32_e64 v33, v33, 0, s[40:41]
	v_cvt_pk_bf16_f32 v10, v22, v23
	v_cvt_pk_bf16_f32 v11, v24, v25
	v_cvt_pk_bf16_f32 v12, v26, v27
	v_cvt_pk_bf16_f32 v13, v28, v29
	v_cvt_pk_bf16_f32 v14, v30, v31
	v_cvt_pk_bf16_f32 v15, v32, v33
	v_cvt_pk_bf16_f32 v16, v34, v35
	v_cvt_pk_bf16_f32 v17, v36, v37
	s_barrier
	ds_write2_b64 v42, v[2:3], v[4:5] offset1:4
	ds_write2_b64 v42, v[6:7], v[8:9] offset0:8 offset1:12
	ds_write2_b64 v42, v[10:11], v[12:13] offset0:16 offset1:20
	ds_write2_b64 v42, v[14:15], v[16:17] offset0:24 offset1:28
	s_waitcnt lgkmcnt(0)
	s_barrier
	ds_read_b128 v[2:5], v114
	ds_read_b128 v[6:9], v81 offset:34816
	flat_load_dwordx4 v[136:139], v[58:59]
	flat_load_dwordx4 v[124:127], v[60:61]
	ds_read_b128 v[14:17], v114 offset:4352
	ds_read_b128 v[42:45], v83 offset:34816
	s_waitcnt lgkmcnt(0)
	v_mfma_f32_16x16x32_bf16 v[50:53], v[2:5], v[42:45], 0
	ds_read_b128 v[34:37], v81 offset:47872
	ds_read_b128 v[18:21], v81 offset:39168
	ds_read_b128 v[26:29], v81 offset:43520
	v_mfma_f32_16x16x32_bf16 v[54:57], v[14:17], v[42:45], 0
	ds_read_b128 v[42:45], v85 offset:34816
	ds_read_b128 v[46:49], v102 offset:34816
	s_waitcnt lgkmcnt(0)
	v_mfma_f32_16x16x32_bf16 v[62:65], v[2:5], v[42:45], 0
	v_mfma_f32_16x16x32_bf16 v[98:101], v[14:17], v[42:45], 0
	ds_read_b128 v[42:45], v87 offset:34816
	s_waitcnt lgkmcnt(0)
	v_mfma_f32_16x16x32_bf16 v[116:119], v[2:5], v[42:45], 0
	v_mfma_f32_16x16x32_bf16 v[120:123], v[14:17], v[42:45], 0
	ds_read_b128 v[42:45], v81
	v_mfma_f32_16x16x32_bf16 v[10:13], v[2:5], v[6:9], 0
	v_mfma_f32_16x16x32_bf16 v[6:9], v[14:17], v[6:9], 0
	s_waitcnt vmcnt(0) lgkmcnt(0)
	v_mfma_f32_16x16x32_bf16 v[140:143], v[136:139], v[42:45], v[6:9]
	s_nop 5
	ds_read_b128 v[6:9], v81 offset:4352
	v_mfma_f32_16x16x32_bf16 v[22:25], v[2:5], v[18:21], 0
	v_mfma_f32_16x16x32_bf16 v[18:21], v[14:17], v[18:21], 0
	v_mfma_f32_16x16x32_bf16 v[132:135], v[124:127], v[42:45], v[10:13]
	s_nop 2
	ds_read_b128 v[10:13], v87
	s_waitcnt lgkmcnt(1)
	v_mfma_f32_16x16x32_bf16 v[144:147], v[124:127], v[6:9], v[22:25]
	v_mfma_f32_16x16x32_bf16 v[148:151], v[136:139], v[6:9], v[18:21]
	ds_read_b128 v[6:9], v81 offset:8704
	v_mfma_f32_16x16x32_bf16 v[30:33], v[2:5], v[26:29], 0
	v_mfma_f32_16x16x32_bf16 v[26:29], v[14:17], v[26:29], 0
	v_mfma_f32_16x16x32_bf16 v[38:41], v[2:5], v[34:37], 0
	v_mfma_f32_16x16x32_bf16 v[2:5], v[2:5], v[46:49], 0
	v_mfma_f32_16x16x32_bf16 v[128:131], v[14:17], v[46:49], 0
	s_waitcnt lgkmcnt(0)
	v_mfma_f32_16x16x32_bf16 v[42:45], v[124:127], v[6:9], v[30:33]
	v_mfma_f32_16x16x32_bf16 v[46:49], v[136:139], v[6:9], v[26:29]
	ds_read_b128 v[6:9], v81 offset:13056
	v_mfma_f32_16x16x32_bf16 v[34:37], v[14:17], v[34:37], 0
	s_waitcnt lgkmcnt(0)
	v_mfma_f32_16x16x32_bf16 v[30:33], v[124:127], v[6:9], v[38:41]
	v_mfma_f32_16x16x32_bf16 v[34:37], v[136:139], v[6:9], v[34:37]
	ds_read_b128 v[6:9], v83
	s_nop 0
	ds_read_b128 v[38:41], v102
	s_waitcnt lgkmcnt(1)
	v_mfma_f32_16x16x32_bf16 v[22:25], v[124:127], v[6:9], v[50:53]
	v_mfma_f32_16x16x32_bf16 v[26:29], v[136:139], v[6:9], v[54:57]
	ds_read_b128 v[6:9], v85
	s_waitcnt lgkmcnt(0)
	v_mfma_f32_16x16x32_bf16 v[14:17], v[124:127], v[6:9], v[62:65]
	ds_read_b128 v[54:57], v81 offset:34880
	s_nop 1
	ds_read_b128 v[62:65], v114 offset:64
	v_mfma_f32_16x16x32_bf16 v[18:21], v[136:139], v[6:9], v[98:101]
	s_nop 2
	ds_read_b128 v[98:101], v114 offset:4416
	v_mfma_f32_16x16x32_bf16 v[6:9], v[124:127], v[10:13], v[116:119]
	v_mfma_f32_16x16x32_bf16 v[2:5], v[124:127], v[38:41], v[2:5]
	ds_read_b128 v[124:127], v81 offset:43584
	s_nop 0
	ds_read_b128 v[116:119], v81 offset:39232
	s_waitcnt lgkmcnt(1)
	v_mfma_f32_16x16x32_bf16 v[42:45], v[62:65], v[124:127], v[42:45]
	v_mfma_f32_16x16x32_bf16 v[46:49], v[98:101], v[124:127], v[46:49]
	ds_read_b128 v[124:127], v81 offset:47936
	s_waitcnt lgkmcnt(0)
	v_mfma_f32_16x16x32_bf16 v[30:33], v[62:65], v[124:127], v[30:33]
	v_mfma_f32_16x16x32_bf16 v[34:37], v[98:101], v[124:127], v[34:37]
	ds_read_b128 v[124:127], v83 offset:34880
	s_waitcnt lgkmcnt(0)
	v_mfma_f32_16x16x32_bf16 v[22:25], v[62:65], v[124:127], v[22:25]
	v_mfma_f32_16x16x32_bf16 v[26:29], v[98:101], v[124:127], v[26:29]
	ds_read_b128 v[124:127], v85 offset:34880
	s_waitcnt lgkmcnt(0)
	v_mfma_f32_16x16x32_bf16 v[14:17], v[62:65], v[124:127], v[14:17]
	v_mfma_f32_16x16x32_bf16 v[18:21], v[98:101], v[124:127], v[18:21]
	ds_read_b128 v[124:127], v87 offset:34880
	v_mfma_f32_16x16x32_bf16 v[10:13], v[136:139], v[10:13], v[120:123]
	s_waitcnt lgkmcnt(0)
	v_mfma_f32_16x16x32_bf16 v[6:9], v[62:65], v[124:127], v[6:9]
	v_mfma_f32_16x16x32_bf16 v[10:13], v[98:101], v[124:127], v[10:13]
	ds_read_b128 v[124:127], v102 offset:34880
	v_mfma_f32_16x16x32_bf16 v[38:41], v[136:139], v[38:41], v[128:131]
	flat_load_dwordx4 v[136:139], v[58:59] offset:192
	v_mfma_f32_16x16x32_bf16 v[50:53], v[62:65], v[54:57], v[132:135]
	v_mfma_f32_16x16x32_bf16 v[120:123], v[62:65], v[116:119], v[144:147]
	s_nop 1
	flat_load_dwordx4 v[132:135], v[60:61] offset:192
	s_waitcnt lgkmcnt(0)
	v_mfma_f32_16x16x32_bf16 v[2:5], v[62:65], v[124:127], v[2:5]
	flat_load_dwordx4 v[62:65], v[60:61] offset:64
	v_mfma_f32_16x16x32_bf16 v[38:41], v[98:101], v[124:127], v[38:41]
	flat_load_dwordx4 v[124:127], v[58:59] offset:64
	v_mfma_f32_16x16x32_bf16 v[54:57], v[98:101], v[54:57], v[140:143]
	v_mfma_f32_16x16x32_bf16 v[116:119], v[98:101], v[116:119], v[148:151]
	ds_read_b128 v[98:101], v81 offset:64
	s_waitcnt vmcnt(0) lgkmcnt(0)
	v_mfma_f32_16x16x32_bf16 v[50:53], v[62:65], v[98:101], v[50:53]
	v_mfma_f32_16x16x32_bf16 v[54:57], v[124:127], v[98:101], v[54:57]
	ds_read_b128 v[98:101], v81 offset:4416
	s_waitcnt lgkmcnt(0)
	v_mfma_f32_16x16x32_bf16 v[120:123], v[62:65], v[98:101], v[120:123]
	v_mfma_f32_16x16x32_bf16 v[98:101], v[124:127], v[98:101], v[116:119]
	s_nop 2
	ds_read_b128 v[116:119], v81 offset:8768
	s_waitcnt lgkmcnt(0)
	v_mfma_f32_16x16x32_bf16 v[42:45], v[62:65], v[116:119], v[42:45]
	v_mfma_f32_16x16x32_bf16 v[46:49], v[124:127], v[116:119], v[46:49]
	ds_read_b128 v[116:119], v81 offset:13120
	s_waitcnt lgkmcnt(0)
	v_mfma_f32_16x16x32_bf16 v[30:33], v[62:65], v[116:119], v[30:33]
	v_mfma_f32_16x16x32_bf16 v[34:37], v[124:127], v[116:119], v[34:37]
	ds_read_b128 v[116:119], v83 offset:64
	s_waitcnt lgkmcnt(0)
	v_mfma_f32_16x16x32_bf16 v[22:25], v[62:65], v[116:119], v[22:25]
	v_mfma_f32_16x16x32_bf16 v[26:29], v[124:127], v[116:119], v[26:29]
	ds_read_b128 v[116:119], v85 offset:64
	s_waitcnt lgkmcnt(0)
	v_mfma_f32_16x16x32_bf16 v[14:17], v[62:65], v[116:119], v[14:17]
	v_mfma_f32_16x16x32_bf16 v[18:21], v[124:127], v[116:119], v[18:21]
	ds_read_b128 v[116:119], v87 offset:64
	s_waitcnt lgkmcnt(0)
	v_mfma_f32_16x16x32_bf16 v[6:9], v[62:65], v[116:119], v[6:9]
	v_mfma_f32_16x16x32_bf16 v[10:13], v[124:127], v[116:119], v[10:13]
	ds_read_b128 v[116:119], v102 offset:64
	s_waitcnt lgkmcnt(0)
	v_mfma_f32_16x16x32_bf16 v[2:5], v[62:65], v[116:119], v[2:5]
	ds_read_b128 v[62:65], v114 offset:128
	v_mfma_f32_16x16x32_bf16 v[38:41], v[124:127], v[116:119], v[38:41]
	ds_read_b128 v[124:127], v114 offset:4480
	ds_read_b128 v[116:119], v81 offset:34944
	s_waitcnt lgkmcnt(0)
	v_mfma_f32_16x16x32_bf16 v[50:53], v[62:65], v[116:119], v[50:53]
	v_mfma_f32_16x16x32_bf16 v[54:57], v[124:127], v[116:119], v[54:57]
	ds_read_b128 v[116:119], v81 offset:39296
	s_waitcnt lgkmcnt(0)
	v_mfma_f32_16x16x32_bf16 v[120:123], v[62:65], v[116:119], v[120:123]
	v_mfma_f32_16x16x32_bf16 v[98:101], v[124:127], v[116:119], v[98:101]
	ds_read_b128 v[116:119], v81 offset:43648
	s_waitcnt lgkmcnt(0)
	v_mfma_f32_16x16x32_bf16 v[42:45], v[62:65], v[116:119], v[42:45]
	v_mfma_f32_16x16x32_bf16 v[46:49], v[124:127], v[116:119], v[46:49]
	ds_read_b128 v[116:119], v81 offset:48000
	s_waitcnt lgkmcnt(0)
	v_mfma_f32_16x16x32_bf16 v[30:33], v[62:65], v[116:119], v[30:33]
	v_mfma_f32_16x16x32_bf16 v[34:37], v[124:127], v[116:119], v[34:37]
	ds_read_b128 v[116:119], v83 offset:34944
	s_waitcnt lgkmcnt(0)
	v_mfma_f32_16x16x32_bf16 v[22:25], v[62:65], v[116:119], v[22:25]
	v_mfma_f32_16x16x32_bf16 v[26:29], v[124:127], v[116:119], v[26:29]
	ds_read_b128 v[116:119], v85 offset:34944
	s_waitcnt lgkmcnt(0)
	v_mfma_f32_16x16x32_bf16 v[14:17], v[62:65], v[116:119], v[14:17]
	v_mfma_f32_16x16x32_bf16 v[18:21], v[124:127], v[116:119], v[18:21]
	ds_read_b128 v[116:119], v87 offset:34944
	s_waitcnt lgkmcnt(0)
	v_mfma_f32_16x16x32_bf16 v[6:9], v[62:65], v[116:119], v[6:9]
	v_mfma_f32_16x16x32_bf16 v[10:13], v[124:127], v[116:119], v[10:13]
	ds_read_b128 v[116:119], v102 offset:34944
	s_waitcnt lgkmcnt(0)
	v_mfma_f32_16x16x32_bf16 v[2:5], v[62:65], v[116:119], v[2:5]
	flat_load_dwordx4 v[62:65], v[60:61] offset:128
	v_mfma_f32_16x16x32_bf16 v[38:41], v[124:127], v[116:119], v[38:41]
	flat_load_dwordx4 v[124:127], v[58:59] offset:128
	ds_read_b128 v[116:119], v81 offset:128
	s_waitcnt vmcnt(0) lgkmcnt(0)
	v_mfma_f32_16x16x32_bf16 v[50:53], v[62:65], v[116:119], v[50:53]
	v_mfma_f32_16x16x32_bf16 v[54:57], v[124:127], v[116:119], v[54:57]
	ds_read_b128 v[116:119], v81 offset:4480
	s_waitcnt lgkmcnt(0)
	v_mfma_f32_16x16x32_bf16 v[120:123], v[62:65], v[116:119], v[120:123]
	v_mfma_f32_16x16x32_bf16 v[98:101], v[124:127], v[116:119], v[98:101]
	ds_read_b128 v[116:119], v81 offset:8832
	s_waitcnt lgkmcnt(0)
	v_mfma_f32_16x16x32_bf16 v[42:45], v[62:65], v[116:119], v[42:45]
	v_mfma_f32_16x16x32_bf16 v[46:49], v[124:127], v[116:119], v[46:49]
	ds_read_b128 v[116:119], v81 offset:13184
	s_waitcnt lgkmcnt(0)
	v_mfma_f32_16x16x32_bf16 v[30:33], v[62:65], v[116:119], v[30:33]
	v_mfma_f32_16x16x32_bf16 v[34:37], v[124:127], v[116:119], v[34:37]
	ds_read_b128 v[116:119], v83 offset:128
	s_waitcnt lgkmcnt(0)
	v_mfma_f32_16x16x32_bf16 v[22:25], v[62:65], v[116:119], v[22:25]
	v_mfma_f32_16x16x32_bf16 v[26:29], v[124:127], v[116:119], v[26:29]
	ds_read_b128 v[116:119], v85 offset:128
	s_waitcnt lgkmcnt(0)
	v_mfma_f32_16x16x32_bf16 v[14:17], v[62:65], v[116:119], v[14:17]
	v_mfma_f32_16x16x32_bf16 v[18:21], v[124:127], v[116:119], v[18:21]
	ds_read_b128 v[116:119], v87 offset:128
	s_waitcnt lgkmcnt(0)
	v_mfma_f32_16x16x32_bf16 v[6:9], v[62:65], v[116:119], v[6:9]
	v_mfma_f32_16x16x32_bf16 v[10:13], v[124:127], v[116:119], v[10:13]
	ds_read_b128 v[116:119], v102 offset:128
	s_waitcnt lgkmcnt(0)
	v_mfma_f32_16x16x32_bf16 v[2:5], v[62:65], v[116:119], v[2:5]
	ds_read_b128 v[62:65], v114 offset:192
	v_mfma_f32_16x16x32_bf16 v[38:41], v[124:127], v[116:119], v[38:41]
	ds_read_b128 v[124:127], v114 offset:4544
	ds_read_b128 v[116:119], v81 offset:35008
	s_waitcnt lgkmcnt(0)
	v_mfma_f32_16x16x32_bf16 v[50:53], v[62:65], v[116:119], v[50:53]
	v_mfma_f32_16x16x32_bf16 v[54:57], v[124:127], v[116:119], v[54:57]
	ds_read_b128 v[116:119], v81 offset:39360
	s_waitcnt lgkmcnt(0)
	v_mfma_f32_16x16x32_bf16 v[120:123], v[62:65], v[116:119], v[120:123]
	v_mfma_f32_16x16x32_bf16 v[98:101], v[124:127], v[116:119], v[98:101]
	ds_read_b128 v[116:119], v81 offset:43712
	s_waitcnt lgkmcnt(0)
	v_mfma_f32_16x16x32_bf16 v[42:45], v[62:65], v[116:119], v[42:45]
	v_mfma_f32_16x16x32_bf16 v[116:119], v[124:127], v[116:119], v[46:49]
	s_nop 2
	ds_read_b128 v[46:49], v81 offset:48064
	s_waitcnt lgkmcnt(0)
	v_mfma_f32_16x16x32_bf16 v[30:33], v[62:65], v[46:49], v[30:33]
	v_mfma_f32_16x16x32_bf16 v[34:37], v[124:127], v[46:49], v[34:37]
	ds_read_b128 v[46:49], v83 offset:35008
	s_waitcnt lgkmcnt(0)
	v_mfma_f32_16x16x32_bf16 v[22:25], v[62:65], v[46:49], v[22:25]
	v_mfma_f32_16x16x32_bf16 v[26:29], v[124:127], v[46:49], v[26:29]
	ds_read_b128 v[46:49], v85 offset:35008
	s_waitcnt lgkmcnt(0)
	v_mfma_f32_16x16x32_bf16 v[14:17], v[62:65], v[46:49], v[14:17]
	v_mfma_f32_16x16x32_bf16 v[18:21], v[124:127], v[46:49], v[18:21]
	ds_read_b128 v[46:49], v87 offset:35008
	s_waitcnt lgkmcnt(0)
	v_mfma_f32_16x16x32_bf16 v[128:131], v[62:65], v[46:49], v[6:9]
	v_mfma_f32_16x16x32_bf16 v[6:9], v[124:127], v[46:49], v[10:13]
	s_nop 2
	ds_read_b128 v[10:13], v102 offset:35008
	s_waitcnt lgkmcnt(0)
	v_mfma_f32_16x16x32_bf16 v[2:5], v[62:65], v[10:13], v[2:5]
	v_mfma_f32_16x16x32_bf16 v[124:127], v[124:127], v[10:13], v[38:41]
	ds_read_b128 v[10:13], v81 offset:192
	s_waitcnt lgkmcnt(0)
	v_mfma_f32_16x16x32_bf16 v[62:65], v[132:135], v[10:13], v[50:53]
	v_mfma_f32_16x16x32_bf16 v[58:61], v[136:139], v[10:13], v[54:57]
	ds_read_b128 v[10:13], v81 offset:4544
	s_waitcnt lgkmcnt(0)
	v_mfma_f32_16x16x32_bf16 v[54:57], v[132:135], v[10:13], v[120:123]
	v_mfma_f32_16x16x32_bf16 v[50:53], v[136:139], v[10:13], v[98:101]
	ds_read_b128 v[10:13], v81 offset:8896
	s_waitcnt lgkmcnt(0)
	v_mfma_f32_16x16x32_bf16 v[46:49], v[132:135], v[10:13], v[42:45]
	v_and_b32_e32 v98, 64, v195
	v_add_u32_e32 v98, 64, v98
	v_cmp_lt_i32_e32 vcc, v95, v98
	v_mfma_f32_16x16x32_bf16 v[42:45], v[136:139], v[10:13], v[116:119]
	ds_read_b128 v[10:13], v81 offset:13248
	s_nop 1
	ds_read_b128 v[116:119], v102 offset:192
	s_waitcnt lgkmcnt(1)
	v_mfma_f32_16x16x32_bf16 v[38:41], v[132:135], v[10:13], v[30:33]
	v_mfma_f32_16x16x32_bf16 v[34:37], v[136:139], v[10:13], v[34:37]
	ds_read_b128 v[10:13], v83 offset:192
	s_waitcnt lgkmcnt(0)
	v_mfma_f32_16x16x32_bf16 v[30:33], v[132:135], v[10:13], v[22:25]
	v_mfma_f32_16x16x32_bf16 v[26:29], v[136:139], v[10:13], v[26:29]
	ds_read_b128 v[10:13], v85 offset:192
	s_waitcnt lgkmcnt(0)
	v_mfma_f32_16x16x32_bf16 v[22:25], v[132:135], v[10:13], v[14:17]
	v_mfma_f32_16x16x32_bf16 v[18:21], v[136:139], v[10:13], v[18:21]
	ds_read_b128 v[10:13], v87 offset:192
	s_waitcnt lgkmcnt(0)
	v_mfma_f32_16x16x32_bf16 v[14:17], v[132:135], v[10:13], v[128:131]
	v_mfma_f32_16x16x32_bf16 v[10:13], v[136:139], v[10:13], v[6:9]
	s_nop 2
	v_cndmask_b32_e32 v6, v195, v95, vcc
	v_lshlrev_b32_e32 v95, 2, v6
	v_mfma_f32_16x16x32_bf16 v[6:9], v[132:135], v[116:119], v[2:5]
	s_nop 2
	v_mul_f32_e32 v2, v63, v63
	v_mul_f32_e32 v3, v65, v65
	v_mul_f32_e32 v4, v59, v59
	v_mul_f32_e32 v5, v61, v61
	v_fmac_f32_e32 v2, v62, v62
	v_fmac_f32_e32 v3, v64, v64
	v_fmac_f32_e32 v4, v58, v58
	v_fmac_f32_e32 v5, v60, v60
	v_add_f32_e32 v2, v2, v3
	v_add_f32_e32 v3, v4, v5
	v_add_f32_e32 v2, v2, v3
	ds_bpermute_b32 v3, v95, v2
	v_xor_b32_e32 v4, 32, v195
	v_cmp_lt_i32_e32 vcc, v4, v98
	s_waitcnt lgkmcnt(0)
	v_add_f32_e32 v99, v2, v3
	v_cndmask_b32_e32 v4, v195, v4, vcc
	v_lshlrev_b32_e32 v98, 2, v4
	ds_bpermute_b32 v100, v98, v99
	v_mfma_f32_16x16x32_bf16 v[2:5], v[136:139], v[116:119], v[124:127]
	s_and_saveexec_b64 s[34:35], s[6:7]
	s_cbranch_execz .LBB0_81
	s_waitcnt lgkmcnt(0)
	v_add_f32_e32 v99, v99, v100
	ds_write_b32 v104, v99

.Leg_cont:
	v_lshlrev_b64 v[144:145], 11, v[248:249]
	v_lshl_add_u64 v[144:145], s[22:23], 0, v[144:145]
	v_lshl_add_u64 v[140:141], v[246:247], 1, v[144:145]
	v_mov_b64_e32 v[142:143], v[140:141]
	s_mov_b64 s[34:35], 0x8000
	s_mov_b64 s[38:39], 0x28000
	s_cmp_gt_i32 s78, 0
	s_cselect_b64 s[6:7], -1, 0
	s_cmp_gt_i32 s78, 0
	s_cbranch_scc0 .Leg_z0
	global_load_dwordx4 v[210:213], v[138:139], off
	global_load_dwordx4 v[214:217], v[140:141], off
	global_load_dwordx4 v[218:221], v[138:139], off offset:256
	global_load_dwordx4 v[222:225], v[140:141], off offset:256
	v_lshl_add_u64 v[138:139], v[138:139], 0, s[0:1]
	v_lshl_add_u64 v[140:141], v[140:141], 0, s[34:35]
	global_load_dwordx4 v[226:229], v[138:139], off
	global_load_dwordx4 v[230:233], v[140:141], off
	global_load_dwordx4 v[234:237], v[138:139], off offset:256
	global_load_dwordx4 v[238:241], v[140:141], off offset:256
	v_lshl_add_u64 v[138:139], v[138:139], 0, s[0:1]
	v_lshl_add_u64 v[140:141], v[140:141], 0, s[34:35]
	global_load_dwordx4 v[182:185], v[138:139], off
	global_load_dwordx4 v[186:189], v[140:141], off
	global_load_dwordx4 v[190:193], v[138:139], off offset:256
	global_load_dwordx4 v[242:245], v[140:141], off offset:256
	v_lshl_add_u64 v[138:139], v[138:139], 0, s[0:1]
	v_lshl_add_u64 v[140:141], v[140:141], 0, s[34:35]
	s_waitcnt vmcnt(8)
	v_lshlrev_b32_e32 v130, 16, v210
	v_and_b32_e32 v131, 0xffff0000, v210
	v_lshlrev_b32_e32 v132, 16, v211
	v_and_b32_e32 v133, 0xffff0000, v211
	v_mul_f32_e32 v130, 0xbfb8aa3b, v130
	v_mul_f32_e32 v131, 0xbfb8aa3b, v131
	v_mul_f32_e32 v132, 0xbfb8aa3b, v132
	v_mul_f32_e32 v133, 0xbfb8aa3b, v133
	v_exp_f32_e32 v130, v130
	v_exp_f32_e32 v131, v131
	v_exp_f32_e32 v132, v132
	v_exp_f32_e32 v133, v133
	v_lshlrev_b32_e32 v134, 16, v214
	v_and_b32_e32 v135, 0xffff0000, v214
	v_lshlrev_b32_e32 v136, 16, v215
	v_and_b32_e32 v137, 0xffff0000, v215
	v_add_f32_e32 v130, 1.0, v130
	v_add_f32_e32 v131, 1.0, v131
	v_add_f32_e32 v132, 1.0, v132
	v_add_f32_e32 v133, 1.0, v133
	v_rcp_f32_e32 v130, v130
	v_rcp_f32_e32 v131, v131
	v_rcp_f32_e32 v132, v132
	v_rcp_f32_e32 v133, v133
	s_nop 0
	v_fmac_f32_e32 v134, v126, v130
	v_fmac_f32_e32 v135, v127, v131
	v_fmac_f32_e32 v136, v128, v132
	v_fmac_f32_e32 v137, v129, v133
	v_cvt_pk_bf16_f32 v126, v134, v135
	v_cvt_pk_bf16_f32 v127, v136, v137
	v_lshlrev_b32_e32 v130, 16, v212
	v_and_b32_e32 v131, 0xffff0000, v212
	v_lshlrev_b32_e32 v132, 16, v213
	v_and_b32_e32 v133, 0xffff0000, v213
	v_mul_f32_e32 v130, 0xbfb8aa3b, v130
	v_mul_f32_e32 v131, 0xbfb8aa3b, v131
	v_mul_f32_e32 v132, 0xbfb8aa3b, v132
	v_mul_f32_e32 v133, 0xbfb8aa3b, v133
	v_exp_f32_e32 v130, v130
	v_exp_f32_e32 v131, v131
	v_exp_f32_e32 v132, v132
	v_exp_f32_e32 v133, v133
	v_lshlrev_b32_e32 v134, 16, v216
	v_and_b32_e32 v135, 0xffff0000, v216
	v_lshlrev_b32_e32 v136, 16, v217
	v_and_b32_e32 v137, 0xffff0000, v217
	v_add_f32_e32 v130, 1.0, v130
	v_add_f32_e32 v131, 1.0, v131
	v_add_f32_e32 v132, 1.0, v132
	v_add_f32_e32 v133, 1.0, v133
	v_rcp_f32_e32 v130, v130
	v_rcp_f32_e32 v131, v131
	v_rcp_f32_e32 v132, v132
	v_rcp_f32_e32 v133, v133
	s_nop 0
	v_fmac_f32_e32 v134, v122, v130
	v_fmac_f32_e32 v135, v123, v131
	v_fmac_f32_e32 v136, v124, v132
	v_fmac_f32_e32 v137, v125, v133
	v_cvt_pk_bf16_f32 v128, v134, v135
	v_cvt_pk_bf16_f32 v129, v136, v137
	v_lshlrev_b32_e32 v130, 16, v218
	v_and_b32_e32 v131, 0xffff0000, v218
	v_lshlrev_b32_e32 v132, 16, v219
	v_and_b32_e32 v133, 0xffff0000, v219
	v_mul_f32_e32 v130, 0xbfb8aa3b, v130
	v_mul_f32_e32 v131, 0xbfb8aa3b, v131
	v_mul_f32_e32 v132, 0xbfb8aa3b, v132
	v_mul_f32_e32 v133, 0xbfb8aa3b, v133
	v_exp_f32_e32 v130, v130
	v_exp_f32_e32 v131, v131
	v_exp_f32_e32 v132, v132
	v_exp_f32_e32 v133, v133
	v_lshlrev_b32_e32 v134, 16, v222
	v_and_b32_e32 v135, 0xffff0000, v222
	v_lshlrev_b32_e32 v136, 16, v223
	v_and_b32_e32 v137, 0xffff0000, v223
	v_add_f32_e32 v130, 1.0, v130
	v_add_f32_e32 v131, 1.0, v131
	v_add_f32_e32 v132, 1.0, v132
	v_add_f32_e32 v133, 1.0, v133
	v_rcp_f32_e32 v130, v130
	v_rcp_f32_e32 v131, v131
	v_rcp_f32_e32 v132, v132
	v_rcp_f32_e32 v133, v133
	s_nop 0
	v_fmac_f32_e32 v134, v118, v130
	v_fmac_f32_e32 v135, v119, v131
	v_fmac_f32_e32 v136, v120, v132
	v_fmac_f32_e32 v137, v121, v133
	v_cvt_pk_bf16_f32 v118, v134, v135
	v_cvt_pk_bf16_f32 v119, v136, v137
	v_lshlrev_b32_e32 v130, 16, v220
	v_and_b32_e32 v131, 0xffff0000, v220
	v_lshlrev_b32_e32 v132, 16, v221
	v_and_b32_e32 v133, 0xffff0000, v221
	v_mul_f32_e32 v130, 0xbfb8aa3b, v130
	v_mul_f32_e32 v131, 0xbfb8aa3b, v131
	v_mul_f32_e32 v132, 0xbfb8aa3b, v132
	v_mul_f32_e32 v133, 0xbfb8aa3b, v133
	v_exp_f32_e32 v130, v130
	v_exp_f32_e32 v131, v131
	v_exp_f32_e32 v132, v132
	v_exp_f32_e32 v133, v133
	v_lshlrev_b32_e32 v134, 16, v224
	v_and_b32_e32 v135, 0xffff0000, v224
	v_lshlrev_b32_e32 v136, 16, v225
	v_and_b32_e32 v137, 0xffff0000, v225
	v_add_f32_e32 v130, 1.0, v130
	v_add_f32_e32 v131, 1.0, v131
	v_add_f32_e32 v132, 1.0, v132
	v_add_f32_e32 v133, 1.0, v133
	v_rcp_f32_e32 v130, v130
	v_rcp_f32_e32 v131, v131
	v_rcp_f32_e32 v132, v132
	v_rcp_f32_e32 v133, v133
	s_nop 0
	v_fmac_f32_e32 v134, v114, v130
	v_fmac_f32_e32 v135, v115, v131
	v_fmac_f32_e32 v136, v116, v132
	v_fmac_f32_e32 v137, v117, v133
	v_cvt_pk_bf16_f32 v120, v134, v135
	v_cvt_pk_bf16_f32 v121, v136, v137
	global_load_dwordx4 v[210:213], v[138:139], off
	global_load_dwordx4 v[214:217], v[140:141], off
	global_load_dwordx4 v[218:221], v[138:139], off offset:256
	global_load_dwordx4 v[222:225], v[140:141], off offset:256
	v_lshl_add_u64 v[138:139], v[138:139], 0, s[4:5]
	v_lshl_add_u64 v[140:141], v[140:141], 0, s[38:39]
	global_store_dwordx4 v[142:143], v[126:129], off
	global_store_dwordx4 v[142:143], v[118:121], off offset:256
	v_lshl_add_u64 v[142:143], v[142:143], 0, s[34:35]
	s_waitcnt vmcnt(10)
	v_lshlrev_b32_e32 v130, 16, v226
	v_and_b32_e32 v131, 0xffff0000, v226
	v_lshlrev_b32_e32 v132, 16, v227
	v_and_b32_e32 v133, 0xffff0000, v227
	v_mul_f32_e32 v130, 0xbfb8aa3b, v130
	v_mul_f32_e32 v131, 0xbfb8aa3b, v131
	v_mul_f32_e32 v132, 0xbfb8aa3b, v132
	v_mul_f32_e32 v133, 0xbfb8aa3b, v133
	v_exp_f32_e32 v130, v130
	v_exp_f32_e32 v131, v131
	v_exp_f32_e32 v132, v132
	v_exp_f32_e32 v133, v133
	v_lshlrev_b32_e32 v134, 16, v230
	v_and_b32_e32 v135, 0xffff0000, v230
	v_lshlrev_b32_e32 v136, 16, v231
	v_and_b32_e32 v137, 0xffff0000, v231
	v_add_f32_e32 v130, 1.0, v130
	v_add_f32_e32 v131, 1.0, v131
	v_add_f32_e32 v132, 1.0, v132
	v_add_f32_e32 v133, 1.0, v133
	v_rcp_f32_e32 v130, v130
	v_rcp_f32_e32 v131, v131
	v_rcp_f32_e32 v132, v132
	v_rcp_f32_e32 v133, v133
	s_nop 0
	v_fmac_f32_e32 v134, v110, v130
	v_fmac_f32_e32 v135, v111, v131
	v_fmac_f32_e32 v136, v112, v132
	v_fmac_f32_e32 v137, v113, v133
	v_cvt_pk_bf16_f32 v110, v134, v135
	v_cvt_pk_bf16_f32 v111, v136, v137
	v_lshlrev_b32_e32 v130, 16, v228
	v_and_b32_e32 v131, 0xffff0000, v228
	v_lshlrev_b32_e32 v132, 16, v229
	v_and_b32_e32 v133, 0xffff0000, v229
	v_mul_f32_e32 v130, 0xbfb8aa3b, v130
	v_mul_f32_e32 v131, 0xbfb8aa3b, v131
	v_mul_f32_e32 v132, 0xbfb8aa3b, v132
	v_mul_f32_e32 v133, 0xbfb8aa3b, v133
	v_exp_f32_e32 v130, v130
	v_exp_f32_e32 v131, v131
	v_exp_f32_e32 v132, v132
	v_exp_f32_e32 v133, v133
	v_lshlrev_b32_e32 v134, 16, v232
	v_and_b32_e32 v135, 0xffff0000, v232
	v_lshlrev_b32_e32 v136, 16, v233
	v_and_b32_e32 v137, 0xffff0000, v233
	v_add_f32_e32 v130, 1.0, v130
	v_add_f32_e32 v131, 1.0, v131
	v_add_f32_e32 v132, 1.0, v132
	v_add_f32_e32 v133, 1.0, v133
	v_rcp_f32_e32 v130, v130
	v_rcp_f32_e32 v131, v131
	v_rcp_f32_e32 v132, v132
	v_rcp_f32_e32 v133, v133
	s_nop 0
	v_fmac_f32_e32 v134, v106, v130
	v_fmac_f32_e32 v135, v107, v131
	v_fmac_f32_e32 v136, v108, v132
	v_fmac_f32_e32 v137, v109, v133
	v_cvt_pk_bf16_f32 v112, v134, v135
	v_cvt_pk_bf16_f32 v113, v136, v137
	v_lshlrev_b32_e32 v130, 16, v234
	v_and_b32_e32 v131, 0xffff0000, v234
	v_lshlrev_b32_e32 v132, 16, v235
	v_and_b32_e32 v133, 0xffff0000, v235
	v_mul_f32_e32 v130, 0xbfb8aa3b, v130
	v_mul_f32_e32 v131, 0xbfb8aa3b, v131
	v_mul_f32_e32 v132, 0xbfb8aa3b, v132
	v_mul_f32_e32 v133, 0xbfb8aa3b, v133
	v_exp_f32_e32 v130, v130
	v_exp_f32_e32 v131, v131
	v_exp_f32_e32 v132, v132
	v_exp_f32_e32 v133, v133
	v_lshlrev_b32_e32 v134, 16, v238
	v_and_b32_e32 v135, 0xffff0000, v238
	v_lshlrev_b32_e32 v136, 16, v239
	v_and_b32_e32 v137, 0xffff0000, v239
	v_add_f32_e32 v130, 1.0, v130
	v_add_f32_e32 v131, 1.0, v131
	v_add_f32_e32 v132, 1.0, v132
	v_add_f32_e32 v133, 1.0, v133
	v_rcp_f32_e32 v130, v130
	v_rcp_f32_e32 v131, v131
	v_rcp_f32_e32 v132, v132
	v_rcp_f32_e32 v133, v133
	s_nop 0
	v_fmac_f32_e32 v134, v102, v130
	v_fmac_f32_e32 v135, v103, v131
	v_fmac_f32_e32 v136, v104, v132
	v_fmac_f32_e32 v137, v105, v133
	v_cvt_pk_bf16_f32 v102, v134, v135
	v_cvt_pk_bf16_f32 v103, v136, v137
	v_lshlrev_b32_e32 v130, 16, v236
	v_and_b32_e32 v131, 0xffff0000, v236
	v_lshlrev_b32_e32 v132, 16, v237
	v_and_b32_e32 v133, 0xffff0000, v237
	v_mul_f32_e32 v130, 0xbfb8aa3b, v130
	v_mul_f32_e32 v131, 0xbfb8aa3b, v131
	v_mul_f32_e32 v132, 0xbfb8aa3b, v132
	v_mul_f32_e32 v133, 0xbfb8aa3b, v133
	v_exp_f32_e32 v130, v130
	v_exp_f32_e32 v131, v131
	v_exp_f32_e32 v132, v132
	v_exp_f32_e32 v133, v133
	v_lshlrev_b32_e32 v134, 16, v240
	v_and_b32_e32 v135, 0xffff0000, v240
	v_lshlrev_b32_e32 v136, 16, v241
	v_and_b32_e32 v137, 0xffff0000, v241
	v_add_f32_e32 v130, 1.0, v130
	v_add_f32_e32 v131, 1.0, v131
	v_add_f32_e32 v132, 1.0, v132
	v_add_f32_e32 v133, 1.0, v133
	v_rcp_f32_e32 v130, v130
	v_rcp_f32_e32 v131, v131
	v_rcp_f32_e32 v132, v132
	v_rcp_f32_e32 v133, v133
	s_nop 0
	v_fmac_f32_e32 v134, v98, v130
	v_fmac_f32_e32 v135, v99, v131
	v_fmac_f32_e32 v136, v100, v132
	v_fmac_f32_e32 v137, v101, v133
	v_cvt_pk_bf16_f32 v104, v134, v135
	v_cvt_pk_bf16_f32 v105, v136, v137
	global_load_dwordx4 v[226:229], v[138:139], off
	global_load_dwordx4 v[230:233], v[140:141], off
	global_load_dwordx4 v[234:237], v[138:139], off offset:256
	global_load_dwordx4 v[238:241], v[140:141], off offset:256
	v_lshl_add_u64 v[138:139], v[138:139], 0, s[0:1]
	v_lshl_add_u64 v[140:141], v[140:141], 0, s[34:35]
	global_store_dwordx4 v[142:143], v[110:113], off
	global_store_dwordx4 v[142:143], v[102:105], off offset:256
	v_lshl_add_u64 v[142:143], v[142:143], 0, s[34:35]
	s_waitcnt vmcnt(12)
	v_lshlrev_b32_e32 v130, 16, v182
	v_and_b32_e32 v131, 0xffff0000, v182
	v_lshlrev_b32_e32 v132, 16, v183
	v_and_b32_e32 v133, 0xffff0000, v183
	v_mul_f32_e32 v130, 0xbfb8aa3b, v130
	v_mul_f32_e32 v131, 0xbfb8aa3b, v131
	v_mul_f32_e32 v132, 0xbfb8aa3b, v132
	v_mul_f32_e32 v133, 0xbfb8aa3b, v133
	v_exp_f32_e32 v130, v130
	v_exp_f32_e32 v131, v131
	v_exp_f32_e32 v132, v132
	v_exp_f32_e32 v133, v133
	v_lshlrev_b32_e32 v134, 16, v186
	v_and_b32_e32 v135, 0xffff0000, v186
	v_lshlrev_b32_e32 v136, 16, v187
	v_and_b32_e32 v137, 0xffff0000, v187
	v_add_f32_e32 v130, 1.0, v130
	v_add_f32_e32 v131, 1.0, v131
	v_add_f32_e32 v132, 1.0, v132
	v_add_f32_e32 v133, 1.0, v133
	v_rcp_f32_e32 v130, v130
	v_rcp_f32_e32 v131, v131
	v_rcp_f32_e32 v132, v132
	v_rcp_f32_e32 v133, v133
	s_nop 0
	v_fmac_f32_e32 v134, v94, v130
	v_fmac_f32_e32 v135, v95, v131
	v_fmac_f32_e32 v136, v96, v132
	v_fmac_f32_e32 v137, v97, v133
	v_cvt_pk_bf16_f32 v94, v134, v135
	v_cvt_pk_bf16_f32 v95, v136, v137
	v_lshlrev_b32_e32 v130, 16, v184
	v_and_b32_e32 v131, 0xffff0000, v184
	v_lshlrev_b32_e32 v132, 16, v185
	v_and_b32_e32 v133, 0xffff0000, v185
	v_mul_f32_e32 v130, 0xbfb8aa3b, v130
	v_mul_f32_e32 v131, 0xbfb8aa3b, v131
	v_mul_f32_e32 v132, 0xbfb8aa3b, v132
	v_mul_f32_e32 v133, 0xbfb8aa3b, v133
	v_exp_f32_e32 v130, v130
	v_exp_f32_e32 v131, v131
	v_exp_f32_e32 v132, v132
	v_exp_f32_e32 v133, v133
	v_lshlrev_b32_e32 v134, 16, v188
	v_and_b32_e32 v135, 0xffff0000, v188
	v_lshlrev_b32_e32 v136, 16, v189
	v_and_b32_e32 v137, 0xffff0000, v189
	v_add_f32_e32 v130, 1.0, v130
	v_add_f32_e32 v131, 1.0, v131
	v_add_f32_e32 v132, 1.0, v132
	v_add_f32_e32 v133, 1.0, v133
	v_rcp_f32_e32 v130, v130
	v_rcp_f32_e32 v131, v131
	v_rcp_f32_e32 v132, v132
	v_rcp_f32_e32 v133, v133
	s_nop 0
	v_fmac_f32_e32 v134, v90, v130
	v_fmac_f32_e32 v135, v91, v131
	v_fmac_f32_e32 v136, v92, v132
	v_fmac_f32_e32 v137, v93, v133
	v_cvt_pk_bf16_f32 v96, v134, v135
	v_cvt_pk_bf16_f32 v97, v136, v137
	v_lshlrev_b32_e32 v130, 16, v190
	v_and_b32_e32 v131, 0xffff0000, v190
	v_lshlrev_b32_e32 v132, 16, v191
	v_and_b32_e32 v133, 0xffff0000, v191
	v_mul_f32_e32 v130, 0xbfb8aa3b, v130
	v_mul_f32_e32 v131, 0xbfb8aa3b, v131
	v_mul_f32_e32 v132, 0xbfb8aa3b, v132
	v_mul_f32_e32 v133, 0xbfb8aa3b, v133
	v_exp_f32_e32 v130, v130
	v_exp_f32_e32 v131, v131
	v_exp_f32_e32 v132, v132
	v_exp_f32_e32 v133, v133
	v_lshlrev_b32_e32 v134, 16, v242
	v_and_b32_e32 v135, 0xffff0000, v242
	v_lshlrev_b32_e32 v136, 16, v243
	v_and_b32_e32 v137, 0xffff0000, v243
	v_add_f32_e32 v130, 1.0, v130
	v_add_f32_e32 v131, 1.0, v131
	v_add_f32_e32 v132, 1.0, v132
	v_add_f32_e32 v133, 1.0, v133
	v_rcp_f32_e32 v130, v130
	v_rcp_f32_e32 v131, v131
	v_rcp_f32_e32 v132, v132
	v_rcp_f32_e32 v133, v133
	s_nop 0
	v_fmac_f32_e32 v134, v86, v130
	v_fmac_f32_e32 v135, v87, v131
	v_fmac_f32_e32 v136, v88, v132
	v_fmac_f32_e32 v137, v89, v133
	v_cvt_pk_bf16_f32 v86, v134, v135
	v_cvt_pk_bf16_f32 v87, v136, v137
	v_lshlrev_b32_e32 v130, 16, v192
	v_and_b32_e32 v131, 0xffff0000, v192
	v_lshlrev_b32_e32 v132, 16, v193
	v_and_b32_e32 v133, 0xffff0000, v193
	v_mul_f32_e32 v130, 0xbfb8aa3b, v130
	v_mul_f32_e32 v131, 0xbfb8aa3b, v131
	v_mul_f32_e32 v132, 0xbfb8aa3b, v132
	v_mul_f32_e32 v133, 0xbfb8aa3b, v133
	v_exp_f32_e32 v130, v130
	v_exp_f32_e32 v131, v131
	v_exp_f32_e32 v132, v132
	v_exp_f32_e32 v133, v133
	v_lshlrev_b32_e32 v134, 16, v244
	v_and_b32_e32 v135, 0xffff0000, v244
	v_lshlrev_b32_e32 v136, 16, v245
	v_and_b32_e32 v137, 0xffff0000, v245
	v_add_f32_e32 v130, 1.0, v130
	v_add_f32_e32 v131, 1.0, v131
	v_add_f32_e32 v132, 1.0, v132
	v_add_f32_e32 v133, 1.0, v133
	v_rcp_f32_e32 v130, v130
	v_rcp_f32_e32 v131, v131
	v_rcp_f32_e32 v132, v132
	v_rcp_f32_e32 v133, v133
	s_nop 0
	v_fmac_f32_e32 v134, v82, v130
	v_fmac_f32_e32 v135, v83, v131
	v_fmac_f32_e32 v136, v84, v132
	v_fmac_f32_e32 v137, v85, v133
	v_cvt_pk_bf16_f32 v88, v134, v135
	v_cvt_pk_bf16_f32 v89, v136, v137
	global_load_dwordx4 v[182:185], v[138:139], off
	global_load_dwordx4 v[186:189], v[140:141], off
	global_load_dwordx4 v[190:193], v[138:139], off offset:256
	global_load_dwordx4 v[242:245], v[140:141], off offset:256
	v_lshl_add_u64 v[138:139], v[138:139], 0, s[0:1]
	v_lshl_add_u64 v[140:141], v[140:141], 0, s[34:35]
	global_store_dwordx4 v[142:143], v[94:97], off
	global_store_dwordx4 v[142:143], v[86:89], off offset:256
	v_lshl_add_u64 v[142:143], v[142:143], 0, s[34:35]
	s_waitcnt vmcnt(14)
	v_lshlrev_b32_e32 v130, 16, v210
	v_and_b32_e32 v131, 0xffff0000, v210
	v_lshlrev_b32_e32 v132, 16, v211
	v_and_b32_e32 v133, 0xffff0000, v211
	v_mul_f32_e32 v130, 0xbfb8aa3b, v130
	v_mul_f32_e32 v131, 0xbfb8aa3b, v131
	v_mul_f32_e32 v132, 0xbfb8aa3b, v132
	v_mul_f32_e32 v133, 0xbfb8aa3b, v133
	v_exp_f32_e32 v130, v130
	v_exp_f32_e32 v131, v131
	v_exp_f32_e32 v132, v132
	v_exp_f32_e32 v133, v133
	v_lshlrev_b32_e32 v134, 16, v214
	v_and_b32_e32 v135, 0xffff0000, v214
	v_lshlrev_b32_e32 v136, 16, v215
	v_and_b32_e32 v137, 0xffff0000, v215
	v_add_f32_e32 v130, 1.0, v130
	v_add_f32_e32 v131, 1.0, v131
	v_add_f32_e32 v132, 1.0, v132
	v_add_f32_e32 v133, 1.0, v133
	v_rcp_f32_e32 v130, v130
	v_rcp_f32_e32 v131, v131
	v_rcp_f32_e32 v132, v132
	v_rcp_f32_e32 v133, v133
	s_nop 0
	v_fmac_f32_e32 v134, v78, v130
	v_fmac_f32_e32 v135, v79, v131
	v_fmac_f32_e32 v136, v80, v132
	v_fmac_f32_e32 v137, v81, v133
	v_cvt_pk_bf16_f32 v78, v134, v135
	v_cvt_pk_bf16_f32 v79, v136, v137
	v_lshlrev_b32_e32 v130, 16, v212
	v_and_b32_e32 v131, 0xffff0000, v212
	v_lshlrev_b32_e32 v132, 16, v213
	v_and_b32_e32 v133, 0xffff0000, v213
	v_mul_f32_e32 v130, 0xbfb8aa3b, v130
	v_mul_f32_e32 v131, 0xbfb8aa3b, v131
	v_mul_f32_e32 v132, 0xbfb8aa3b, v132
	v_mul_f32_e32 v133, 0xbfb8aa3b, v133
	v_exp_f32_e32 v130, v130
	v_exp_f32_e32 v131, v131
	v_exp_f32_e32 v132, v132
	v_exp_f32_e32 v133, v133
	v_lshlrev_b32_e32 v134, 16, v216
	v_and_b32_e32 v135, 0xffff0000, v216
	v_lshlrev_b32_e32 v136, 16, v217
	v_and_b32_e32 v137, 0xffff0000, v217
	v_add_f32_e32 v130, 1.0, v130
	v_add_f32_e32 v131, 1.0, v131
	v_add_f32_e32 v132, 1.0, v132
	v_add_f32_e32 v133, 1.0, v133
	v_rcp_f32_e32 v130, v130
	v_rcp_f32_e32 v131, v131
	v_rcp_f32_e32 v132, v132
	v_rcp_f32_e32 v133, v133
	s_nop 0
	v_fmac_f32_e32 v134, v74, v130
	v_fmac_f32_e32 v135, v75, v131
	v_fmac_f32_e32 v136, v76, v132
	v_fmac_f32_e32 v137, v77, v133
	v_cvt_pk_bf16_f32 v80, v134, v135
	v_cvt_pk_bf16_f32 v81, v136, v137
	v_lshlrev_b32_e32 v130, 16, v218
	v_and_b32_e32 v131, 0xffff0000, v218
	v_lshlrev_b32_e32 v132, 16, v219
	v_and_b32_e32 v133, 0xffff0000, v219
	v_mul_f32_e32 v130, 0xbfb8aa3b, v130
	v_mul_f32_e32 v131, 0xbfb8aa3b, v131
	v_mul_f32_e32 v132, 0xbfb8aa3b, v132
	v_mul_f32_e32 v133, 0xbfb8aa3b, v133
	v_exp_f32_e32 v130, v130
	v_exp_f32_e32 v131, v131
	v_exp_f32_e32 v132, v132
	v_exp_f32_e32 v133, v133
	v_lshlrev_b32_e32 v134, 16, v222
	v_and_b32_e32 v135, 0xffff0000, v222
	v_lshlrev_b32_e32 v136, 16, v223
	v_and_b32_e32 v137, 0xffff0000, v223
	v_add_f32_e32 v130, 1.0, v130
	v_add_f32_e32 v131, 1.0, v131
	v_add_f32_e32 v132, 1.0, v132
	v_add_f32_e32 v133, 1.0, v133
	v_rcp_f32_e32 v130, v130
	v_rcp_f32_e32 v131, v131
	v_rcp_f32_e32 v132, v132
	v_rcp_f32_e32 v133, v133
	s_nop 0
	v_fmac_f32_e32 v134, v70, v130
	v_fmac_f32_e32 v135, v71, v131
	v_fmac_f32_e32 v136, v72, v132
	v_fmac_f32_e32 v137, v73, v133
	v_cvt_pk_bf16_f32 v70, v134, v135
	v_cvt_pk_bf16_f32 v71, v136, v137
	v_lshlrev_b32_e32 v130, 16, v220
	v_and_b32_e32 v131, 0xffff0000, v220
	v_lshlrev_b32_e32 v132, 16, v221
	v_and_b32_e32 v133, 0xffff0000, v221
	v_mul_f32_e32 v130, 0xbfb8aa3b, v130
	v_mul_f32_e32 v131, 0xbfb8aa3b, v131
	v_mul_f32_e32 v132, 0xbfb8aa3b, v132
	v_mul_f32_e32 v133, 0xbfb8aa3b, v133
	v_exp_f32_e32 v130, v130
	v_exp_f32_e32 v131, v131
	v_exp_f32_e32 v132, v132
	v_exp_f32_e32 v133, v133
	v_lshlrev_b32_e32 v134, 16, v224
	v_and_b32_e32 v135, 0xffff0000, v224
	v_lshlrev_b32_e32 v136, 16, v225
	v_and_b32_e32 v137, 0xffff0000, v225
	v_add_f32_e32 v130, 1.0, v130
	v_add_f32_e32 v131, 1.0, v131
	v_add_f32_e32 v132, 1.0, v132
	v_add_f32_e32 v133, 1.0, v133
	v_rcp_f32_e32 v130, v130
	v_rcp_f32_e32 v131, v131
	v_rcp_f32_e32 v132, v132
	v_rcp_f32_e32 v133, v133
	s_nop 0
	v_fmac_f32_e32 v134, v66, v130
	v_fmac_f32_e32 v135, v67, v131
	v_fmac_f32_e32 v136, v68, v132
	v_fmac_f32_e32 v137, v69, v133
	v_cvt_pk_bf16_f32 v72, v134, v135
	v_cvt_pk_bf16_f32 v73, v136, v137
	global_load_dwordx4 v[210:213], v[138:139], off
	global_load_dwordx4 v[214:217], v[140:141], off
	global_load_dwordx4 v[218:221], v[138:139], off offset:256
	global_load_dwordx4 v[222:225], v[140:141], off offset:256
	v_lshl_add_u64 v[138:139], v[138:139], 0, s[0:1]
	v_lshl_add_u64 v[140:141], v[140:141], 0, s[34:35]
	global_store_dwordx4 v[142:143], v[78:81], off
	global_store_dwordx4 v[142:143], v[70:73], off offset:256
	v_lshl_add_u64 v[142:143], v[142:143], 0, s[38:39]
	s_waitcnt vmcnt(14)
	v_lshlrev_b32_e32 v130, 16, v226
	v_and_b32_e32 v131, 0xffff0000, v226
	v_lshlrev_b32_e32 v132, 16, v227
	v_and_b32_e32 v133, 0xffff0000, v227
	v_mul_f32_e32 v130, 0xbfb8aa3b, v130
	v_mul_f32_e32 v131, 0xbfb8aa3b, v131
	v_mul_f32_e32 v132, 0xbfb8aa3b, v132
	v_mul_f32_e32 v133, 0xbfb8aa3b, v133
	v_exp_f32_e32 v130, v130
	v_exp_f32_e32 v131, v131
	v_exp_f32_e32 v132, v132
	v_exp_f32_e32 v133, v133
	v_lshlrev_b32_e32 v134, 16, v230
	v_and_b32_e32 v135, 0xffff0000, v230
	v_lshlrev_b32_e32 v136, 16, v231
	v_and_b32_e32 v137, 0xffff0000, v231
	v_add_f32_e32 v130, 1.0, v130
	v_add_f32_e32 v131, 1.0, v131
	v_add_f32_e32 v132, 1.0, v132
	v_add_f32_e32 v133, 1.0, v133
	v_rcp_f32_e32 v130, v130
	v_rcp_f32_e32 v131, v131
	v_rcp_f32_e32 v132, v132
	v_rcp_f32_e32 v133, v133
	s_nop 0
	v_fmac_f32_e32 v134, v62, v130
	v_fmac_f32_e32 v135, v63, v131
	v_fmac_f32_e32 v136, v64, v132
	v_fmac_f32_e32 v137, v65, v133
	v_cvt_pk_bf16_f32 v62, v134, v135
	v_cvt_pk_bf16_f32 v63, v136, v137
	v_lshlrev_b32_e32 v130, 16, v228
	v_and_b32_e32 v131, 0xffff0000, v228
	v_lshlrev_b32_e32 v132, 16, v229
	v_and_b32_e32 v133, 0xffff0000, v229
	v_mul_f32_e32 v130, 0xbfb8aa3b, v130
	v_mul_f32_e32 v131, 0xbfb8aa3b, v131
	v_mul_f32_e32 v132, 0xbfb8aa3b, v132
	v_mul_f32_e32 v133, 0xbfb8aa3b, v133
	v_exp_f32_e32 v130, v130
	v_exp_f32_e32 v131, v131
	v_exp_f32_e32 v132, v132
	v_exp_f32_e32 v133, v133
	v_lshlrev_b32_e32 v134, 16, v232
	v_and_b32_e32 v135, 0xffff0000, v232
	v_lshlrev_b32_e32 v136, 16, v233
	v_and_b32_e32 v137, 0xffff0000, v233
	v_add_f32_e32 v130, 1.0, v130
	v_add_f32_e32 v131, 1.0, v131
	v_add_f32_e32 v132, 1.0, v132
	v_add_f32_e32 v133, 1.0, v133
	v_rcp_f32_e32 v130, v130
	v_rcp_f32_e32 v131, v131
	v_rcp_f32_e32 v132, v132
	v_rcp_f32_e32 v133, v133
	s_nop 0
	v_fmac_f32_e32 v134, v58, v130
	v_fmac_f32_e32 v135, v59, v131
	v_fmac_f32_e32 v136, v60, v132
	v_fmac_f32_e32 v137, v61, v133
	v_cvt_pk_bf16_f32 v64, v134, v135
	v_cvt_pk_bf16_f32 v65, v136, v137
	v_lshlrev_b32_e32 v130, 16, v234
	v_and_b32_e32 v131, 0xffff0000, v234
	v_lshlrev_b32_e32 v132, 16, v235
	v_and_b32_e32 v133, 0xffff0000, v235
	v_mul_f32_e32 v130, 0xbfb8aa3b, v130
	v_mul_f32_e32 v131, 0xbfb8aa3b, v131
	v_mul_f32_e32 v132, 0xbfb8aa3b, v132
	v_mul_f32_e32 v133, 0xbfb8aa3b, v133
	v_exp_f32_e32 v130, v130
	v_exp_f32_e32 v131, v131
	v_exp_f32_e32 v132, v132
	v_exp_f32_e32 v133, v133
	v_lshlrev_b32_e32 v134, 16, v238
	v_and_b32_e32 v135, 0xffff0000, v238
	v_lshlrev_b32_e32 v136, 16, v239
	v_and_b32_e32 v137, 0xffff0000, v239
	v_add_f32_e32 v130, 1.0, v130
	v_add_f32_e32 v131, 1.0, v131
	v_add_f32_e32 v132, 1.0, v132
	v_add_f32_e32 v133, 1.0, v133
	v_rcp_f32_e32 v130, v130
	v_rcp_f32_e32 v131, v131
	v_rcp_f32_e32 v132, v132
	v_rcp_f32_e32 v133, v133
	s_nop 0
	v_fmac_f32_e32 v134, v54, v130
	v_fmac_f32_e32 v135, v55, v131
	v_fmac_f32_e32 v136, v56, v132
	v_fmac_f32_e32 v137, v57, v133
	v_cvt_pk_bf16_f32 v54, v134, v135
	v_cvt_pk_bf16_f32 v55, v136, v137
	v_lshlrev_b32_e32 v130, 16, v236
	v_and_b32_e32 v131, 0xffff0000, v236
	v_lshlrev_b32_e32 v132, 16, v237
	v_and_b32_e32 v133, 0xffff0000, v237
	v_mul_f32_e32 v130, 0xbfb8aa3b, v130
	v_mul_f32_e32 v131, 0xbfb8aa3b, v131
	v_mul_f32_e32 v132, 0xbfb8aa3b, v132
	v_mul_f32_e32 v133, 0xbfb8aa3b, v133
	v_exp_f32_e32 v130, v130
	v_exp_f32_e32 v131, v131
	v_exp_f32_e32 v132, v132
	v_exp_f32_e32 v133, v133
	v_lshlrev_b32_e32 v134, 16, v240
	v_and_b32_e32 v135, 0xffff0000, v240
	v_lshlrev_b32_e32 v136, 16, v241
	v_and_b32_e32 v137, 0xffff0000, v241
	v_add_f32_e32 v130, 1.0, v130
	v_add_f32_e32 v131, 1.0, v131
	v_add_f32_e32 v132, 1.0, v132
	v_add_f32_e32 v133, 1.0, v133
	v_rcp_f32_e32 v130, v130
	v_rcp_f32_e32 v131, v131
	v_rcp_f32_e32 v132, v132
	v_rcp_f32_e32 v133, v133
	s_nop 0
	v_fmac_f32_e32 v134, v50, v130
	v_fmac_f32_e32 v135, v51, v131
	v_fmac_f32_e32 v136, v52, v132
	v_fmac_f32_e32 v137, v53, v133
	v_cvt_pk_bf16_f32 v56, v134, v135
	v_cvt_pk_bf16_f32 v57, v136, v137
	global_load_dwordx4 v[226:229], v[138:139], off
	global_load_dwordx4 v[230:233], v[140:141], off
	global_load_dwordx4 v[234:237], v[138:139], off offset:256
	global_load_dwordx4 v[238:241], v[140:141], off offset:256
	global_store_dwordx4 v[142:143], v[62:65], off
	global_store_dwordx4 v[142:143], v[54:57], off offset:256
	v_lshl_add_u64 v[142:143], v[142:143], 0, s[34:35]
	s_waitcnt vmcnt(14)
	v_lshlrev_b32_e32 v130, 16, v182
	v_and_b32_e32 v131, 0xffff0000, v182
	v_lshlrev_b32_e32 v132, 16, v183
	v_and_b32_e32 v133, 0xffff0000, v183
	v_mul_f32_e32 v130, 0xbfb8aa3b, v130
	v_mul_f32_e32 v131, 0xbfb8aa3b, v131
	v_mul_f32_e32 v132, 0xbfb8aa3b, v132
	v_mul_f32_e32 v133, 0xbfb8aa3b, v133
	v_exp_f32_e32 v130, v130
	v_exp_f32_e32 v131, v131
	v_exp_f32_e32 v132, v132
	v_exp_f32_e32 v133, v133
	v_lshlrev_b32_e32 v134, 16, v186
	v_and_b32_e32 v135, 0xffff0000, v186
	v_lshlrev_b32_e32 v136, 16, v187
	v_and_b32_e32 v137, 0xffff0000, v187
	v_add_f32_e32 v130, 1.0, v130
	v_add_f32_e32 v131, 1.0, v131
	v_add_f32_e32 v132, 1.0, v132
	v_add_f32_e32 v133, 1.0, v133
	v_rcp_f32_e32 v130, v130
	v_rcp_f32_e32 v131, v131
	v_rcp_f32_e32 v132, v132
	v_rcp_f32_e32 v133, v133
	s_nop 0
	v_fmac_f32_e32 v134, v46, v130
	v_fmac_f32_e32 v135, v47, v131
	v_fmac_f32_e32 v136, v48, v132
	v_fmac_f32_e32 v137, v49, v133
	v_cvt_pk_bf16_f32 v46, v134, v135
	v_cvt_pk_bf16_f32 v47, v136, v137
	v_lshlrev_b32_e32 v130, 16, v184
	v_and_b32_e32 v131, 0xffff0000, v184
	v_lshlrev_b32_e32 v132, 16, v185
	v_and_b32_e32 v133, 0xffff0000, v185
	v_mul_f32_e32 v130, 0xbfb8aa3b, v130
	v_mul_f32_e32 v131, 0xbfb8aa3b, v131
	v_mul_f32_e32 v132, 0xbfb8aa3b, v132
	v_mul_f32_e32 v133, 0xbfb8aa3b, v133
	v_exp_f32_e32 v130, v130
	v_exp_f32_e32 v131, v131
	v_exp_f32_e32 v132, v132
	v_exp_f32_e32 v133, v133
	v_lshlrev_b32_e32 v134, 16, v188
	v_and_b32_e32 v135, 0xffff0000, v188
	v_lshlrev_b32_e32 v136, 16, v189
	v_and_b32_e32 v137, 0xffff0000, v189
	v_add_f32_e32 v130, 1.0, v130
	v_add_f32_e32 v131, 1.0, v131
	v_add_f32_e32 v132, 1.0, v132
	v_add_f32_e32 v133, 1.0, v133
	v_rcp_f32_e32 v130, v130
	v_rcp_f32_e32 v131, v131
	v_rcp_f32_e32 v132, v132
	v_rcp_f32_e32 v133, v133
	s_nop 0
	v_fmac_f32_e32 v134, v42, v130
	v_fmac_f32_e32 v135, v43, v131
	v_fmac_f32_e32 v136, v44, v132
	v_fmac_f32_e32 v137, v45, v133
	v_cvt_pk_bf16_f32 v48, v134, v135
	v_cvt_pk_bf16_f32 v49, v136, v137
	v_lshlrev_b32_e32 v130, 16, v190
	v_and_b32_e32 v131, 0xffff0000, v190
	v_lshlrev_b32_e32 v132, 16, v191
	v_and_b32_e32 v133, 0xffff0000, v191
	v_mul_f32_e32 v130, 0xbfb8aa3b, v130
	v_mul_f32_e32 v131, 0xbfb8aa3b, v131
	v_mul_f32_e32 v132, 0xbfb8aa3b, v132
	v_mul_f32_e32 v133, 0xbfb8aa3b, v133
	v_exp_f32_e32 v130, v130
	v_exp_f32_e32 v131, v131
	v_exp_f32_e32 v132, v132
	v_exp_f32_e32 v133, v133
	v_lshlrev_b32_e32 v134, 16, v242
	v_and_b32_e32 v135, 0xffff0000, v242
	v_lshlrev_b32_e32 v136, 16, v243
	v_and_b32_e32 v137, 0xffff0000, v243
	v_add_f32_e32 v130, 1.0, v130
	v_add_f32_e32 v131, 1.0, v131
	v_add_f32_e32 v132, 1.0, v132
	v_add_f32_e32 v133, 1.0, v133
	v_rcp_f32_e32 v130, v130
	v_rcp_f32_e32 v131, v131
	v_rcp_f32_e32 v132, v132
	v_rcp_f32_e32 v133, v133
	s_nop 0
	v_fmac_f32_e32 v134, v38, v130
	v_fmac_f32_e32 v135, v39, v131
	v_fmac_f32_e32 v136, v40, v132
	v_fmac_f32_e32 v137, v41, v133
	v_cvt_pk_bf16_f32 v38, v134, v135
	v_cvt_pk_bf16_f32 v39, v136, v137
	v_lshlrev_b32_e32 v130, 16, v192
	v_and_b32_e32 v131, 0xffff0000, v192
	v_lshlrev_b32_e32 v132, 16, v193
	v_and_b32_e32 v133, 0xffff0000, v193
	v_mul_f32_e32 v130, 0xbfb8aa3b, v130
	v_mul_f32_e32 v131, 0xbfb8aa3b, v131
	v_mul_f32_e32 v132, 0xbfb8aa3b, v132
	v_mul_f32_e32 v133, 0xbfb8aa3b, v133
	v_exp_f32_e32 v130, v130
	v_exp_f32_e32 v131, v131
	v_exp_f32_e32 v132, v132
	v_exp_f32_e32 v133, v133
	v_lshlrev_b32_e32 v134, 16, v244
	v_and_b32_e32 v135, 0xffff0000, v244
	v_lshlrev_b32_e32 v136, 16, v245
	v_and_b32_e32 v137, 0xffff0000, v245
	v_add_f32_e32 v130, 1.0, v130
	v_add_f32_e32 v131, 1.0, v131
	v_add_f32_e32 v132, 1.0, v132
	v_add_f32_e32 v133, 1.0, v133
	v_rcp_f32_e32 v130, v130
	v_rcp_f32_e32 v131, v131
	v_rcp_f32_e32 v132, v132
	v_rcp_f32_e32 v133, v133
	s_nop 0
	v_fmac_f32_e32 v134, v34, v130
	v_fmac_f32_e32 v135, v35, v131
	v_fmac_f32_e32 v136, v36, v132
	v_fmac_f32_e32 v137, v37, v133
	v_cvt_pk_bf16_f32 v40, v134, v135
	v_cvt_pk_bf16_f32 v41, v136, v137
	global_store_dwordx4 v[142:143], v[46:49], off
	global_store_dwordx4 v[142:143], v[38:41], off offset:256
	v_lshl_add_u64 v[142:143], v[142:143], 0, s[34:35]
	s_waitcnt vmcnt(10)
	v_lshlrev_b32_e32 v130, 16, v210
	v_and_b32_e32 v131, 0xffff0000, v210
	v_lshlrev_b32_e32 v132, 16, v211
	v_and_b32_e32 v133, 0xffff0000, v211
	v_mul_f32_e32 v130, 0xbfb8aa3b, v130
	v_mul_f32_e32 v131, 0xbfb8aa3b, v131
	v_mul_f32_e32 v132, 0xbfb8aa3b, v132
	v_mul_f32_e32 v133, 0xbfb8aa3b, v133
	v_exp_f32_e32 v130, v130
	v_exp_f32_e32 v131, v131
	v_exp_f32_e32 v132, v132
	v_exp_f32_e32 v133, v133
	v_lshlrev_b32_e32 v134, 16, v214
	v_and_b32_e32 v135, 0xffff0000, v214
	v_lshlrev_b32_e32 v136, 16, v215
	v_and_b32_e32 v137, 0xffff0000, v215
	v_add_f32_e32 v130, 1.0, v130
	v_add_f32_e32 v131, 1.0, v131
	v_add_f32_e32 v132, 1.0, v132
	v_add_f32_e32 v133, 1.0, v133
	v_rcp_f32_e32 v130, v130
	v_rcp_f32_e32 v131, v131
	v_rcp_f32_e32 v132, v132
	v_rcp_f32_e32 v133, v133
	s_nop 0
	v_fmac_f32_e32 v134, v30, v130
	v_fmac_f32_e32 v135, v31, v131
	v_fmac_f32_e32 v136, v32, v132
	v_fmac_f32_e32 v137, v33, v133
	v_cvt_pk_bf16_f32 v30, v134, v135
	v_cvt_pk_bf16_f32 v31, v136, v137
	v_lshlrev_b32_e32 v130, 16, v212
	v_and_b32_e32 v131, 0xffff0000, v212
	v_lshlrev_b32_e32 v132, 16, v213
	v_and_b32_e32 v133, 0xffff0000, v213
	v_mul_f32_e32 v130, 0xbfb8aa3b, v130
	v_mul_f32_e32 v131, 0xbfb8aa3b, v131
	v_mul_f32_e32 v132, 0xbfb8aa3b, v132
	v_mul_f32_e32 v133, 0xbfb8aa3b, v133
	v_exp_f32_e32 v130, v130
	v_exp_f32_e32 v131, v131
	v_exp_f32_e32 v132, v132
	v_exp_f32_e32 v133, v133
	v_lshlrev_b32_e32 v134, 16, v216
	v_and_b32_e32 v135, 0xffff0000, v216
	v_lshlrev_b32_e32 v136, 16, v217
	v_and_b32_e32 v137, 0xffff0000, v217
	v_add_f32_e32 v130, 1.0, v130
	v_add_f32_e32 v131, 1.0, v131
	v_add_f32_e32 v132, 1.0, v132
	v_add_f32_e32 v133, 1.0, v133
	v_rcp_f32_e32 v130, v130
	v_rcp_f32_e32 v131, v131
	v_rcp_f32_e32 v132, v132
	v_rcp_f32_e32 v133, v133
	s_nop 0
	v_fmac_f32_e32 v134, v26, v130
	v_fmac_f32_e32 v135, v27, v131
	v_fmac_f32_e32 v136, v28, v132
	v_fmac_f32_e32 v137, v29, v133
	v_cvt_pk_bf16_f32 v32, v134, v135
	v_cvt_pk_bf16_f32 v33, v136, v137
	v_lshlrev_b32_e32 v130, 16, v218
	v_and_b32_e32 v131, 0xffff0000, v218
	v_lshlrev_b32_e32 v132, 16, v219
	v_and_b32_e32 v133, 0xffff0000, v219
	v_mul_f32_e32 v130, 0xbfb8aa3b, v130
	v_mul_f32_e32 v131, 0xbfb8aa3b, v131
	v_mul_f32_e32 v132, 0xbfb8aa3b, v132
	v_mul_f32_e32 v133, 0xbfb8aa3b, v133
	v_exp_f32_e32 v130, v130
	v_exp_f32_e32 v131, v131
	v_exp_f32_e32 v132, v132
	v_exp_f32_e32 v133, v133
	v_lshlrev_b32_e32 v134, 16, v222
	v_and_b32_e32 v135, 0xffff0000, v222
	v_lshlrev_b32_e32 v136, 16, v223
	v_and_b32_e32 v137, 0xffff0000, v223
	v_add_f32_e32 v130, 1.0, v130
	v_add_f32_e32 v131, 1.0, v131
	v_add_f32_e32 v132, 1.0, v132
	v_add_f32_e32 v133, 1.0, v133
	v_rcp_f32_e32 v130, v130
	v_rcp_f32_e32 v131, v131
	v_rcp_f32_e32 v132, v132
	v_rcp_f32_e32 v133, v133
	s_nop 0
	v_fmac_f32_e32 v134, v22, v130
	v_fmac_f32_e32 v135, v23, v131
	v_fmac_f32_e32 v136, v24, v132
	v_fmac_f32_e32 v137, v25, v133
	v_cvt_pk_bf16_f32 v22, v134, v135
	v_cvt_pk_bf16_f32 v23, v136, v137
	v_lshlrev_b32_e32 v130, 16, v220
	v_and_b32_e32 v131, 0xffff0000, v220
	v_lshlrev_b32_e32 v132, 16, v221
	v_and_b32_e32 v133, 0xffff0000, v221
	v_mul_f32_e32 v130, 0xbfb8aa3b, v130
	v_mul_f32_e32 v131, 0xbfb8aa3b, v131
	v_mul_f32_e32 v132, 0xbfb8aa3b, v132
	v_mul_f32_e32 v133, 0xbfb8aa3b, v133
	v_exp_f32_e32 v130, v130
	v_exp_f32_e32 v131, v131
	v_exp_f32_e32 v132, v132
	v_exp_f32_e32 v133, v133
	v_lshlrev_b32_e32 v134, 16, v224
	v_and_b32_e32 v135, 0xffff0000, v224
	v_lshlrev_b32_e32 v136, 16, v225
	v_and_b32_e32 v137, 0xffff0000, v225
	v_add_f32_e32 v130, 1.0, v130
	v_add_f32_e32 v131, 1.0, v131
	v_add_f32_e32 v132, 1.0, v132
	v_add_f32_e32 v133, 1.0, v133
	v_rcp_f32_e32 v130, v130
	v_rcp_f32_e32 v131, v131
	v_rcp_f32_e32 v132, v132
	v_rcp_f32_e32 v133, v133
	s_nop 0
	v_fmac_f32_e32 v134, v18, v130
	v_fmac_f32_e32 v135, v19, v131
	v_fmac_f32_e32 v136, v20, v132
	v_fmac_f32_e32 v137, v21, v133
	v_cvt_pk_bf16_f32 v24, v134, v135
	v_cvt_pk_bf16_f32 v25, v136, v137
	global_store_dwordx4 v[142:143], v[30:33], off
	global_store_dwordx4 v[142:143], v[22:25], off offset:256
	v_lshl_add_u64 v[142:143], v[142:143], 0, s[34:35]
	s_waitcnt vmcnt(6)
	v_lshlrev_b32_e32 v130, 16, v226
	v_and_b32_e32 v131, 0xffff0000, v226
	v_lshlrev_b32_e32 v132, 16, v227
	v_and_b32_e32 v133, 0xffff0000, v227
	v_mul_f32_e32 v130, 0xbfb8aa3b, v130
	v_mul_f32_e32 v131, 0xbfb8aa3b, v131
	v_mul_f32_e32 v132, 0xbfb8aa3b, v132
	v_mul_f32_e32 v133, 0xbfb8aa3b, v133
	v_exp_f32_e32 v130, v130
	v_exp_f32_e32 v131, v131
	v_exp_f32_e32 v132, v132
	v_exp_f32_e32 v133, v133
	v_lshlrev_b32_e32 v134, 16, v230
	v_and_b32_e32 v135, 0xffff0000, v230
	v_lshlrev_b32_e32 v136, 16, v231
	v_and_b32_e32 v137, 0xffff0000, v231
	v_add_f32_e32 v130, 1.0, v130
	v_add_f32_e32 v131, 1.0, v131
	v_add_f32_e32 v132, 1.0, v132
	v_add_f32_e32 v133, 1.0, v133
	v_rcp_f32_e32 v130, v130
	v_rcp_f32_e32 v131, v131
	v_rcp_f32_e32 v132, v132
	v_rcp_f32_e32 v133, v133
	s_nop 0
	v_fmac_f32_e32 v134, v14, v130
	v_fmac_f32_e32 v135, v15, v131
	v_fmac_f32_e32 v136, v16, v132
	v_fmac_f32_e32 v137, v17, v133
	v_cvt_pk_bf16_f32 v14, v134, v135
	v_cvt_pk_bf16_f32 v15, v136, v137
	v_lshlrev_b32_e32 v130, 16, v228
	v_and_b32_e32 v131, 0xffff0000, v228
	v_lshlrev_b32_e32 v132, 16, v229
	v_and_b32_e32 v133, 0xffff0000, v229
	v_mul_f32_e32 v130, 0xbfb8aa3b, v130
	v_mul_f32_e32 v131, 0xbfb8aa3b, v131
	v_mul_f32_e32 v132, 0xbfb8aa3b, v132
	v_mul_f32_e32 v133, 0xbfb8aa3b, v133
	v_exp_f32_e32 v130, v130
	v_exp_f32_e32 v131, v131
	v_exp_f32_e32 v132, v132
	v_exp_f32_e32 v133, v133
	v_lshlrev_b32_e32 v134, 16, v232
	v_and_b32_e32 v135, 0xffff0000, v232
	v_lshlrev_b32_e32 v136, 16, v233
	v_and_b32_e32 v137, 0xffff0000, v233
	v_add_f32_e32 v130, 1.0, v130
	v_add_f32_e32 v131, 1.0, v131
	v_add_f32_e32 v132, 1.0, v132
	v_add_f32_e32 v133, 1.0, v133
	v_rcp_f32_e32 v130, v130
	v_rcp_f32_e32 v131, v131
	v_rcp_f32_e32 v132, v132
	v_rcp_f32_e32 v133, v133
	s_nop 0
	v_fmac_f32_e32 v134, v10, v130
	v_fmac_f32_e32 v135, v11, v131
	v_fmac_f32_e32 v136, v12, v132
	v_fmac_f32_e32 v137, v13, v133
	v_cvt_pk_bf16_f32 v16, v134, v135
	v_cvt_pk_bf16_f32 v17, v136, v137
	v_lshlrev_b32_e32 v130, 16, v234
	v_and_b32_e32 v131, 0xffff0000, v234
	v_lshlrev_b32_e32 v132, 16, v235
	v_and_b32_e32 v133, 0xffff0000, v235
	v_mul_f32_e32 v130, 0xbfb8aa3b, v130
	v_mul_f32_e32 v131, 0xbfb8aa3b, v131
	v_mul_f32_e32 v132, 0xbfb8aa3b, v132
	v_mul_f32_e32 v133, 0xbfb8aa3b, v133
	v_exp_f32_e32 v130, v130
	v_exp_f32_e32 v131, v131
	v_exp_f32_e32 v132, v132
	v_exp_f32_e32 v133, v133
	v_lshlrev_b32_e32 v134, 16, v238
	v_and_b32_e32 v135, 0xffff0000, v238
	v_lshlrev_b32_e32 v136, 16, v239
	v_and_b32_e32 v137, 0xffff0000, v239
	v_add_f32_e32 v130, 1.0, v130
	v_add_f32_e32 v131, 1.0, v131
	v_add_f32_e32 v132, 1.0, v132
	v_add_f32_e32 v133, 1.0, v133
	v_rcp_f32_e32 v130, v130
	v_rcp_f32_e32 v131, v131
	v_rcp_f32_e32 v132, v132
	v_rcp_f32_e32 v133, v133
	s_nop 0
	v_fmac_f32_e32 v134, v6, v130
	v_fmac_f32_e32 v135, v7, v131
	v_fmac_f32_e32 v136, v8, v132
	v_fmac_f32_e32 v137, v9, v133
	v_cvt_pk_bf16_f32 v6, v134, v135
	v_cvt_pk_bf16_f32 v7, v136, v137
	v_lshlrev_b32_e32 v130, 16, v236
	v_and_b32_e32 v131, 0xffff0000, v236
	v_lshlrev_b32_e32 v132, 16, v237
	v_and_b32_e32 v133, 0xffff0000, v237
	v_mul_f32_e32 v130, 0xbfb8aa3b, v130
	v_mul_f32_e32 v131, 0xbfb8aa3b, v131
	v_mul_f32_e32 v132, 0xbfb8aa3b, v132
	v_mul_f32_e32 v133, 0xbfb8aa3b, v133
	v_exp_f32_e32 v130, v130
	v_exp_f32_e32 v131, v131
	v_exp_f32_e32 v132, v132
	v_exp_f32_e32 v133, v133
	v_lshlrev_b32_e32 v134, 16, v240
	v_and_b32_e32 v135, 0xffff0000, v240
	v_lshlrev_b32_e32 v136, 16, v241
	v_and_b32_e32 v137, 0xffff0000, v241
	v_add_f32_e32 v130, 1.0, v130
	v_add_f32_e32 v131, 1.0, v131
	v_add_f32_e32 v132, 1.0, v132
	v_add_f32_e32 v133, 1.0, v133
	v_rcp_f32_e32 v130, v130
	v_rcp_f32_e32 v131, v131
	v_rcp_f32_e32 v132, v132
	v_rcp_f32_e32 v133, v133
	s_nop 0
	v_fmac_f32_e32 v134, v2, v130
	v_fmac_f32_e32 v135, v3, v131
	v_fmac_f32_e32 v136, v4, v132
	v_fmac_f32_e32 v137, v5, v133
	v_cvt_pk_bf16_f32 v8, v134, v135
	v_cvt_pk_bf16_f32 v9, v136, v137
	global_store_dwordx4 v[142:143], v[14:17], off
	global_store_dwordx4 v[142:143], v[6:9], off offset:256
	s_branch .Leg_fin
.Leg_z0:
	global_load_dwordx4 v[210:213], v[138:139], off
	global_load_dwordx4 v[218:221], v[138:139], off offset:256
	v_lshl_add_u64 v[138:139], v[138:139], 0, s[0:1]
	v_lshl_add_u64 v[140:141], v[140:141], 0, s[34:35]
	global_load_dwordx4 v[226:229], v[138:139], off
	global_load_dwordx4 v[234:237], v[138:139], off offset:256
	v_lshl_add_u64 v[138:139], v[138:139], 0, s[0:1]
	v_lshl_add_u64 v[140:141], v[140:141], 0, s[34:35]
	global_load_dwordx4 v[182:185], v[138:139], off
	global_load_dwordx4 v[190:193], v[138:139], off offset:256
	v_lshl_add_u64 v[138:139], v[138:139], 0, s[0:1]
	v_lshl_add_u64 v[140:141], v[140:141], 0, s[34:35]
	s_waitcnt vmcnt(4)
	v_mov_b32_e32 v214, 0
	v_mov_b32_e32 v215, 0
	v_mov_b32_e32 v216, 0
	v_mov_b32_e32 v217, 0
	v_lshlrev_b32_e32 v130, 16, v210
	v_and_b32_e32 v131, 0xffff0000, v210
	v_lshlrev_b32_e32 v132, 16, v211
	v_and_b32_e32 v133, 0xffff0000, v211
	v_mul_f32_e32 v130, 0xbfb8aa3b, v130
	v_mul_f32_e32 v131, 0xbfb8aa3b, v131
	v_mul_f32_e32 v132, 0xbfb8aa3b, v132
	v_mul_f32_e32 v133, 0xbfb8aa3b, v133
	v_exp_f32_e32 v130, v130
	v_exp_f32_e32 v131, v131
	v_exp_f32_e32 v132, v132
	v_exp_f32_e32 v133, v133
	v_lshlrev_b32_e32 v134, 16, v214
	v_and_b32_e32 v135, 0xffff0000, v214
	v_lshlrev_b32_e32 v136, 16, v215
	v_and_b32_e32 v137, 0xffff0000, v215
	v_add_f32_e32 v130, 1.0, v130
	v_add_f32_e32 v131, 1.0, v131
	v_add_f32_e32 v132, 1.0, v132
	v_add_f32_e32 v133, 1.0, v133
	v_rcp_f32_e32 v130, v130
	v_rcp_f32_e32 v131, v131
	v_rcp_f32_e32 v132, v132
	v_rcp_f32_e32 v133, v133
	s_nop 0
	v_fmac_f32_e32 v134, v126, v130
	v_fmac_f32_e32 v135, v127, v131
	v_fmac_f32_e32 v136, v128, v132
	v_fmac_f32_e32 v137, v129, v133
	v_cvt_pk_bf16_f32 v126, v134, v135
	v_cvt_pk_bf16_f32 v127, v136, v137
	v_lshlrev_b32_e32 v130, 16, v212
	v_and_b32_e32 v131, 0xffff0000, v212
	v_lshlrev_b32_e32 v132, 16, v213
	v_and_b32_e32 v133, 0xffff0000, v213
	v_mul_f32_e32 v130, 0xbfb8aa3b, v130
	v_mul_f32_e32 v131, 0xbfb8aa3b, v131
	v_mul_f32_e32 v132, 0xbfb8aa3b, v132
	v_mul_f32_e32 v133, 0xbfb8aa3b, v133
	v_exp_f32_e32 v130, v130
	v_exp_f32_e32 v131, v131
	v_exp_f32_e32 v132, v132
	v_exp_f32_e32 v133, v133
	v_lshlrev_b32_e32 v134, 16, v216
	v_and_b32_e32 v135, 0xffff0000, v216
	v_lshlrev_b32_e32 v136, 16, v217
	v_and_b32_e32 v137, 0xffff0000, v217
	v_add_f32_e32 v130, 1.0, v130
	v_add_f32_e32 v131, 1.0, v131
	v_add_f32_e32 v132, 1.0, v132
	v_add_f32_e32 v133, 1.0, v133
	v_rcp_f32_e32 v130, v130
	v_rcp_f32_e32 v131, v131
	v_rcp_f32_e32 v132, v132
	v_rcp_f32_e32 v133, v133
	s_nop 0
	v_fmac_f32_e32 v134, v122, v130
	v_fmac_f32_e32 v135, v123, v131
	v_fmac_f32_e32 v136, v124, v132
	v_fmac_f32_e32 v137, v125, v133
	v_cvt_pk_bf16_f32 v128, v134, v135
	v_cvt_pk_bf16_f32 v129, v136, v137
	v_mov_b32_e32 v222, 0
	v_mov_b32_e32 v223, 0
	v_mov_b32_e32 v224, 0
	v_mov_b32_e32 v225, 0
	v_lshlrev_b32_e32 v130, 16, v218
	v_and_b32_e32 v131, 0xffff0000, v218
	v_lshlrev_b32_e32 v132, 16, v219
	v_and_b32_e32 v133, 0xffff0000, v219
	v_mul_f32_e32 v130, 0xbfb8aa3b, v130
	v_mul_f32_e32 v131, 0xbfb8aa3b, v131
	v_mul_f32_e32 v132, 0xbfb8aa3b, v132
	v_mul_f32_e32 v133, 0xbfb8aa3b, v133
	v_exp_f32_e32 v130, v130
	v_exp_f32_e32 v131, v131
	v_exp_f32_e32 v132, v132
	v_exp_f32_e32 v133, v133
	v_lshlrev_b32_e32 v134, 16, v222
	v_and_b32_e32 v135, 0xffff0000, v222
	v_lshlrev_b32_e32 v136, 16, v223
	v_and_b32_e32 v137, 0xffff0000, v223
	v_add_f32_e32 v130, 1.0, v130
	v_add_f32_e32 v131, 1.0, v131
	v_add_f32_e32 v132, 1.0, v132
	v_add_f32_e32 v133, 1.0, v133
	v_rcp_f32_e32 v130, v130
	v_rcp_f32_e32 v131, v131
	v_rcp_f32_e32 v132, v132
	v_rcp_f32_e32 v133, v133
	s_nop 0
	v_fmac_f32_e32 v134, v118, v130
	v_fmac_f32_e32 v135, v119, v131
	v_fmac_f32_e32 v136, v120, v132
	v_fmac_f32_e32 v137, v121, v133
	v_cvt_pk_bf16_f32 v118, v134, v135
	v_cvt_pk_bf16_f32 v119, v136, v137
	v_lshlrev_b32_e32 v130, 16, v220
	v_and_b32_e32 v131, 0xffff0000, v220
	v_lshlrev_b32_e32 v132, 16, v221
	v_and_b32_e32 v133, 0xffff0000, v221
	v_mul_f32_e32 v130, 0xbfb8aa3b, v130
	v_mul_f32_e32 v131, 0xbfb8aa3b, v131
	v_mul_f32_e32 v132, 0xbfb8aa3b, v132
	v_mul_f32_e32 v133, 0xbfb8aa3b, v133
	v_exp_f32_e32 v130, v130
	v_exp_f32_e32 v131, v131
	v_exp_f32_e32 v132, v132
	v_exp_f32_e32 v133, v133
	v_lshlrev_b32_e32 v134, 16, v224
	v_and_b32_e32 v135, 0xffff0000, v224
	v_lshlrev_b32_e32 v136, 16, v225
	v_and_b32_e32 v137, 0xffff0000, v225
	v_add_f32_e32 v130, 1.0, v130
	v_add_f32_e32 v131, 1.0, v131
	v_add_f32_e32 v132, 1.0, v132
	v_add_f32_e32 v133, 1.0, v133
	v_rcp_f32_e32 v130, v130
	v_rcp_f32_e32 v131, v131
	v_rcp_f32_e32 v132, v132
	v_rcp_f32_e32 v133, v133
	s_nop 0
	v_fmac_f32_e32 v134, v114, v130
	v_fmac_f32_e32 v135, v115, v131
	v_fmac_f32_e32 v136, v116, v132
	v_fmac_f32_e32 v137, v117, v133
	v_cvt_pk_bf16_f32 v120, v134, v135
	v_cvt_pk_bf16_f32 v121, v136, v137
	global_load_dwordx4 v[210:213], v[138:139], off
	global_load_dwordx4 v[218:221], v[138:139], off offset:256
	v_lshl_add_u64 v[138:139], v[138:139], 0, s[4:5]
	v_lshl_add_u64 v[140:141], v[140:141], 0, s[38:39]
	global_store_dwordx4 v[142:143], v[126:129], off
	global_store_dwordx4 v[142:143], v[118:121], off offset:256
	v_lshl_add_u64 v[142:143], v[142:143], 0, s[34:35]
	s_waitcnt vmcnt(6)
	v_mov_b32_e32 v230, 0
	v_mov_b32_e32 v231, 0
	v_mov_b32_e32 v232, 0
	v_mov_b32_e32 v233, 0
	v_lshlrev_b32_e32 v130, 16, v226
	v_and_b32_e32 v131, 0xffff0000, v226
	v_lshlrev_b32_e32 v132, 16, v227
	v_and_b32_e32 v133, 0xffff0000, v227
	v_mul_f32_e32 v130, 0xbfb8aa3b, v130
	v_mul_f32_e32 v131, 0xbfb8aa3b, v131
	v_mul_f32_e32 v132, 0xbfb8aa3b, v132
	v_mul_f32_e32 v133, 0xbfb8aa3b, v133
	v_exp_f32_e32 v130, v130
	v_exp_f32_e32 v131, v131
	v_exp_f32_e32 v132, v132
	v_exp_f32_e32 v133, v133
	v_lshlrev_b32_e32 v134, 16, v230
	v_and_b32_e32 v135, 0xffff0000, v230
	v_lshlrev_b32_e32 v136, 16, v231
	v_and_b32_e32 v137, 0xffff0000, v231
	v_add_f32_e32 v130, 1.0, v130
	v_add_f32_e32 v131, 1.0, v131
	v_add_f32_e32 v132, 1.0, v132
	v_add_f32_e32 v133, 1.0, v133
	v_rcp_f32_e32 v130, v130
	v_rcp_f32_e32 v131, v131
	v_rcp_f32_e32 v132, v132
	v_rcp_f32_e32 v133, v133
	s_nop 0
	v_fmac_f32_e32 v134, v110, v130
	v_fmac_f32_e32 v135, v111, v131
	v_fmac_f32_e32 v136, v112, v132
	v_fmac_f32_e32 v137, v113, v133
	v_cvt_pk_bf16_f32 v110, v134, v135
	v_cvt_pk_bf16_f32 v111, v136, v137
	v_lshlrev_b32_e32 v130, 16, v228
	v_and_b32_e32 v131, 0xffff0000, v228
	v_lshlrev_b32_e32 v132, 16, v229
	v_and_b32_e32 v133, 0xffff0000, v229
	v_mul_f32_e32 v130, 0xbfb8aa3b, v130
	v_mul_f32_e32 v131, 0xbfb8aa3b, v131
	v_mul_f32_e32 v132, 0xbfb8aa3b, v132
	v_mul_f32_e32 v133, 0xbfb8aa3b, v133
	v_exp_f32_e32 v130, v130
	v_exp_f32_e32 v131, v131
	v_exp_f32_e32 v132, v132
	v_exp_f32_e32 v133, v133
	v_lshlrev_b32_e32 v134, 16, v232
	v_and_b32_e32 v135, 0xffff0000, v232
	v_lshlrev_b32_e32 v136, 16, v233
	v_and_b32_e32 v137, 0xffff0000, v233
	v_add_f32_e32 v130, 1.0, v130
	v_add_f32_e32 v131, 1.0, v131
	v_add_f32_e32 v132, 1.0, v132
	v_add_f32_e32 v133, 1.0, v133
	v_rcp_f32_e32 v130, v130
	v_rcp_f32_e32 v131, v131
	v_rcp_f32_e32 v132, v132
	v_rcp_f32_e32 v133, v133
	s_nop 0
	v_fmac_f32_e32 v134, v106, v130
	v_fmac_f32_e32 v135, v107, v131
	v_fmac_f32_e32 v136, v108, v132
	v_fmac_f32_e32 v137, v109, v133
	v_cvt_pk_bf16_f32 v112, v134, v135
	v_cvt_pk_bf16_f32 v113, v136, v137
	v_mov_b32_e32 v238, 0
	v_mov_b32_e32 v239, 0
	v_mov_b32_e32 v240, 0
	v_mov_b32_e32 v241, 0
	v_lshlrev_b32_e32 v130, 16, v234
	v_and_b32_e32 v131, 0xffff0000, v234
	v_lshlrev_b32_e32 v132, 16, v235
	v_and_b32_e32 v133, 0xffff0000, v235
	v_mul_f32_e32 v130, 0xbfb8aa3b, v130
	v_mul_f32_e32 v131, 0xbfb8aa3b, v131
	v_mul_f32_e32 v132, 0xbfb8aa3b, v132
	v_mul_f32_e32 v133, 0xbfb8aa3b, v133
	v_exp_f32_e32 v130, v130
	v_exp_f32_e32 v131, v131
	v_exp_f32_e32 v132, v132
	v_exp_f32_e32 v133, v133
	v_lshlrev_b32_e32 v134, 16, v238
	v_and_b32_e32 v135, 0xffff0000, v238
	v_lshlrev_b32_e32 v136, 16, v239
	v_and_b32_e32 v137, 0xffff0000, v239
	v_add_f32_e32 v130, 1.0, v130
	v_add_f32_e32 v131, 1.0, v131
	v_add_f32_e32 v132, 1.0, v132
	v_add_f32_e32 v133, 1.0, v133
	v_rcp_f32_e32 v130, v130
	v_rcp_f32_e32 v131, v131
	v_rcp_f32_e32 v132, v132
	v_rcp_f32_e32 v133, v133
	s_nop 0
	v_fmac_f32_e32 v134, v102, v130
	v_fmac_f32_e32 v135, v103, v131
	v_fmac_f32_e32 v136, v104, v132
	v_fmac_f32_e32 v137, v105, v133
	v_cvt_pk_bf16_f32 v102, v134, v135
	v_cvt_pk_bf16_f32 v103, v136, v137
	v_lshlrev_b32_e32 v130, 16, v236
	v_and_b32_e32 v131, 0xffff0000, v236
	v_lshlrev_b32_e32 v132, 16, v237
	v_and_b32_e32 v133, 0xffff0000, v237
	v_mul_f32_e32 v130, 0xbfb8aa3b, v130
	v_mul_f32_e32 v131, 0xbfb8aa3b, v131
	v_mul_f32_e32 v132, 0xbfb8aa3b, v132
	v_mul_f32_e32 v133, 0xbfb8aa3b, v133
	v_exp_f32_e32 v130, v130
	v_exp_f32_e32 v131, v131
	v_exp_f32_e32 v132, v132
	v_exp_f32_e32 v133, v133
	v_lshlrev_b32_e32 v134, 16, v240
	v_and_b32_e32 v135, 0xffff0000, v240
	v_lshlrev_b32_e32 v136, 16, v241
	v_and_b32_e32 v137, 0xffff0000, v241
	v_add_f32_e32 v130, 1.0, v130
	v_add_f32_e32 v131, 1.0, v131
	v_add_f32_e32 v132, 1.0, v132
	v_add_f32_e32 v133, 1.0, v133
	v_rcp_f32_e32 v130, v130
	v_rcp_f32_e32 v131, v131
	v_rcp_f32_e32 v132, v132
	v_rcp_f32_e32 v133, v133
	s_nop 0
	v_fmac_f32_e32 v134, v98, v130
	v_fmac_f32_e32 v135, v99, v131
	v_fmac_f32_e32 v136, v100, v132
	v_fmac_f32_e32 v137, v101, v133
	v_cvt_pk_bf16_f32 v104, v134, v135
	v_cvt_pk_bf16_f32 v105, v136, v137
	global_load_dwordx4 v[226:229], v[138:139], off
	global_load_dwordx4 v[234:237], v[138:139], off offset:256
	v_lshl_add_u64 v[138:139], v[138:139], 0, s[0:1]
	v_lshl_add_u64 v[140:141], v[140:141], 0, s[34:35]
	global_store_dwordx4 v[142:143], v[110:113], off
	global_store_dwordx4 v[142:143], v[102:105], off offset:256
	v_lshl_add_u64 v[142:143], v[142:143], 0, s[34:35]
	s_waitcnt vmcnt(8)
	v_mov_b32_e32 v186, 0
	v_mov_b32_e32 v187, 0
	v_mov_b32_e32 v188, 0
	v_mov_b32_e32 v189, 0
	v_lshlrev_b32_e32 v130, 16, v182
	v_and_b32_e32 v131, 0xffff0000, v182
	v_lshlrev_b32_e32 v132, 16, v183
	v_and_b32_e32 v133, 0xffff0000, v183
	v_mul_f32_e32 v130, 0xbfb8aa3b, v130
	v_mul_f32_e32 v131, 0xbfb8aa3b, v131
	v_mul_f32_e32 v132, 0xbfb8aa3b, v132
	v_mul_f32_e32 v133, 0xbfb8aa3b, v133
	v_exp_f32_e32 v130, v130
	v_exp_f32_e32 v131, v131
	v_exp_f32_e32 v132, v132
	v_exp_f32_e32 v133, v133
	v_lshlrev_b32_e32 v134, 16, v186
	v_and_b32_e32 v135, 0xffff0000, v186
	v_lshlrev_b32_e32 v136, 16, v187
	v_and_b32_e32 v137, 0xffff0000, v187
	v_add_f32_e32 v130, 1.0, v130
	v_add_f32_e32 v131, 1.0, v131
	v_add_f32_e32 v132, 1.0, v132
	v_add_f32_e32 v133, 1.0, v133
	v_rcp_f32_e32 v130, v130
	v_rcp_f32_e32 v131, v131
	v_rcp_f32_e32 v132, v132
	v_rcp_f32_e32 v133, v133
	s_nop 0
	v_fmac_f32_e32 v134, v94, v130
	v_fmac_f32_e32 v135, v95, v131
	v_fmac_f32_e32 v136, v96, v132
	v_fmac_f32_e32 v137, v97, v133
	v_cvt_pk_bf16_f32 v94, v134, v135
	v_cvt_pk_bf16_f32 v95, v136, v137
	v_lshlrev_b32_e32 v130, 16, v184
	v_and_b32_e32 v131, 0xffff0000, v184
	v_lshlrev_b32_e32 v132, 16, v185
	v_and_b32_e32 v133, 0xffff0000, v185
	v_mul_f32_e32 v130, 0xbfb8aa3b, v130
	v_mul_f32_e32 v131, 0xbfb8aa3b, v131
	v_mul_f32_e32 v132, 0xbfb8aa3b, v132
	v_mul_f32_e32 v133, 0xbfb8aa3b, v133
	v_exp_f32_e32 v130, v130
	v_exp_f32_e32 v131, v131
	v_exp_f32_e32 v132, v132
	v_exp_f32_e32 v133, v133
	v_lshlrev_b32_e32 v134, 16, v188
	v_and_b32_e32 v135, 0xffff0000, v188
	v_lshlrev_b32_e32 v136, 16, v189
	v_and_b32_e32 v137, 0xffff0000, v189
	v_add_f32_e32 v130, 1.0, v130
	v_add_f32_e32 v131, 1.0, v131
	v_add_f32_e32 v132, 1.0, v132
	v_add_f32_e32 v133, 1.0, v133
	v_rcp_f32_e32 v130, v130
	v_rcp_f32_e32 v131, v131
	v_rcp_f32_e32 v132, v132
	v_rcp_f32_e32 v133, v133
	s_nop 0
	v_fmac_f32_e32 v134, v90, v130
	v_fmac_f32_e32 v135, v91, v131
	v_fmac_f32_e32 v136, v92, v132
	v_fmac_f32_e32 v137, v93, v133
	v_cvt_pk_bf16_f32 v96, v134, v135
	v_cvt_pk_bf16_f32 v97, v136, v137
	v_mov_b32_e32 v242, 0
	v_mov_b32_e32 v243, 0
	v_mov_b32_e32 v244, 0
	v_mov_b32_e32 v245, 0
	v_lshlrev_b32_e32 v130, 16, v190
	v_and_b32_e32 v131, 0xffff0000, v190
	v_lshlrev_b32_e32 v132, 16, v191
	v_and_b32_e32 v133, 0xffff0000, v191
	v_mul_f32_e32 v130, 0xbfb8aa3b, v130
	v_mul_f32_e32 v131, 0xbfb8aa3b, v131
	v_mul_f32_e32 v132, 0xbfb8aa3b, v132
	v_mul_f32_e32 v133, 0xbfb8aa3b, v133
	v_exp_f32_e32 v130, v130
	v_exp_f32_e32 v131, v131
	v_exp_f32_e32 v132, v132
	v_exp_f32_e32 v133, v133
	v_lshlrev_b32_e32 v134, 16, v242
	v_and_b32_e32 v135, 0xffff0000, v242
	v_lshlrev_b32_e32 v136, 16, v243
	v_and_b32_e32 v137, 0xffff0000, v243
	v_add_f32_e32 v130, 1.0, v130
	v_add_f32_e32 v131, 1.0, v131
	v_add_f32_e32 v132, 1.0, v132
	v_add_f32_e32 v133, 1.0, v133
	v_rcp_f32_e32 v130, v130
	v_rcp_f32_e32 v131, v131
	v_rcp_f32_e32 v132, v132
	v_rcp_f32_e32 v133, v133
	s_nop 0
	v_fmac_f32_e32 v134, v86, v130
	v_fmac_f32_e32 v135, v87, v131
	v_fmac_f32_e32 v136, v88, v132
	v_fmac_f32_e32 v137, v89, v133
	v_cvt_pk_bf16_f32 v86, v134, v135
	v_cvt_pk_bf16_f32 v87, v136, v137
	v_lshlrev_b32_e32 v130, 16, v192
	v_and_b32_e32 v131, 0xffff0000, v192
	v_lshlrev_b32_e32 v132, 16, v193
	v_and_b32_e32 v133, 0xffff0000, v193
	v_mul_f32_e32 v130, 0xbfb8aa3b, v130
	v_mul_f32_e32 v131, 0xbfb8aa3b, v131
	v_mul_f32_e32 v132, 0xbfb8aa3b, v132
	v_mul_f32_e32 v133, 0xbfb8aa3b, v133
	v_exp_f32_e32 v130, v130
	v_exp_f32_e32 v131, v131
	v_exp_f32_e32 v132, v132
	v_exp_f32_e32 v133, v133
	v_lshlrev_b32_e32 v134, 16, v244
	v_and_b32_e32 v135, 0xffff0000, v244
	v_lshlrev_b32_e32 v136, 16, v245
	v_and_b32_e32 v137, 0xffff0000, v245
	v_add_f32_e32 v130, 1.0, v130
	v_add_f32_e32 v131, 1.0, v131
	v_add_f32_e32 v132, 1.0, v132
	v_add_f32_e32 v133, 1.0, v133
	v_rcp_f32_e32 v130, v130
	v_rcp_f32_e32 v131, v131
	v_rcp_f32_e32 v132, v132
	v_rcp_f32_e32 v133, v133
	s_nop 0
	v_fmac_f32_e32 v134, v82, v130
	v_fmac_f32_e32 v135, v83, v131
	v_fmac_f32_e32 v136, v84, v132
	v_fmac_f32_e32 v137, v85, v133
	v_cvt_pk_bf16_f32 v88, v134, v135
	v_cvt_pk_bf16_f32 v89, v136, v137
	global_load_dwordx4 v[182:185], v[138:139], off
	global_load_dwordx4 v[190:193], v[138:139], off offset:256
	v_lshl_add_u64 v[138:139], v[138:139], 0, s[0:1]
	v_lshl_add_u64 v[140:141], v[140:141], 0, s[34:35]
	global_store_dwordx4 v[142:143], v[94:97], off
	global_store_dwordx4 v[142:143], v[86:89], off offset:256
	v_lshl_add_u64 v[142:143], v[142:143], 0, s[34:35]
	s_waitcnt vmcnt(10)
	v_mov_b32_e32 v214, 0
	v_mov_b32_e32 v215, 0
	v_mov_b32_e32 v216, 0
	v_mov_b32_e32 v217, 0
	v_lshlrev_b32_e32 v130, 16, v210
	v_and_b32_e32 v131, 0xffff0000, v210
	v_lshlrev_b32_e32 v132, 16, v211
	v_and_b32_e32 v133, 0xffff0000, v211
	v_mul_f32_e32 v130, 0xbfb8aa3b, v130
	v_mul_f32_e32 v131, 0xbfb8aa3b, v131
	v_mul_f32_e32 v132, 0xbfb8aa3b, v132
	v_mul_f32_e32 v133, 0xbfb8aa3b, v133
	v_exp_f32_e32 v130, v130
	v_exp_f32_e32 v131, v131
	v_exp_f32_e32 v132, v132
	v_exp_f32_e32 v133, v133
	v_lshlrev_b32_e32 v134, 16, v214
	v_and_b32_e32 v135, 0xffff0000, v214
	v_lshlrev_b32_e32 v136, 16, v215
	v_and_b32_e32 v137, 0xffff0000, v215
	v_add_f32_e32 v130, 1.0, v130
	v_add_f32_e32 v131, 1.0, v131
	v_add_f32_e32 v132, 1.0, v132
	v_add_f32_e32 v133, 1.0, v133
	v_rcp_f32_e32 v130, v130
	v_rcp_f32_e32 v131, v131
	v_rcp_f32_e32 v132, v132
	v_rcp_f32_e32 v133, v133
	s_nop 0
	v_fmac_f32_e32 v134, v78, v130
	v_fmac_f32_e32 v135, v79, v131
	v_fmac_f32_e32 v136, v80, v132
	v_fmac_f32_e32 v137, v81, v133
	v_cvt_pk_bf16_f32 v78, v134, v135
	v_cvt_pk_bf16_f32 v79, v136, v137
	v_lshlrev_b32_e32 v130, 16, v212
	v_and_b32_e32 v131, 0xffff0000, v212
	v_lshlrev_b32_e32 v132, 16, v213
	v_and_b32_e32 v133, 0xffff0000, v213
	v_mul_f32_e32 v130, 0xbfb8aa3b, v130
	v_mul_f32_e32 v131, 0xbfb8aa3b, v131
	v_mul_f32_e32 v132, 0xbfb8aa3b, v132
	v_mul_f32_e32 v133, 0xbfb8aa3b, v133
	v_exp_f32_e32 v130, v130
	v_exp_f32_e32 v131, v131
	v_exp_f32_e32 v132, v132
	v_exp_f32_e32 v133, v133
	v_lshlrev_b32_e32 v134, 16, v216
	v_and_b32_e32 v135, 0xffff0000, v216
	v_lshlrev_b32_e32 v136, 16, v217
	v_and_b32_e32 v137, 0xffff0000, v217
	v_add_f32_e32 v130, 1.0, v130
	v_add_f32_e32 v131, 1.0, v131
	v_add_f32_e32 v132, 1.0, v132
	v_add_f32_e32 v133, 1.0, v133
	v_rcp_f32_e32 v130, v130
	v_rcp_f32_e32 v131, v131
	v_rcp_f32_e32 v132, v132
	v_rcp_f32_e32 v133, v133
	s_nop 0
	v_fmac_f32_e32 v134, v74, v130
	v_fmac_f32_e32 v135, v75, v131
	v_fmac_f32_e32 v136, v76, v132
	v_fmac_f32_e32 v137, v77, v133
	v_cvt_pk_bf16_f32 v80, v134, v135
	v_cvt_pk_bf16_f32 v81, v136, v137
	v_mov_b32_e32 v222, 0
	v_mov_b32_e32 v223, 0
	v_mov_b32_e32 v224, 0
	v_mov_b32_e32 v225, 0
	v_lshlrev_b32_e32 v130, 16, v218
	v_and_b32_e32 v131, 0xffff0000, v218
	v_lshlrev_b32_e32 v132, 16, v219
	v_and_b32_e32 v133, 0xffff0000, v219
	v_mul_f32_e32 v130, 0xbfb8aa3b, v130
	v_mul_f32_e32 v131, 0xbfb8aa3b, v131
	v_mul_f32_e32 v132, 0xbfb8aa3b, v132
	v_mul_f32_e32 v133, 0xbfb8aa3b, v133
	v_exp_f32_e32 v130, v130
	v_exp_f32_e32 v131, v131
	v_exp_f32_e32 v132, v132
	v_exp_f32_e32 v133, v133
	v_lshlrev_b32_e32 v134, 16, v222
	v_and_b32_e32 v135, 0xffff0000, v222
	v_lshlrev_b32_e32 v136, 16, v223
	v_and_b32_e32 v137, 0xffff0000, v223
	v_add_f32_e32 v130, 1.0, v130
	v_add_f32_e32 v131, 1.0, v131
	v_add_f32_e32 v132, 1.0, v132
	v_add_f32_e32 v133, 1.0, v133
	v_rcp_f32_e32 v130, v130
	v_rcp_f32_e32 v131, v131
	v_rcp_f32_e32 v132, v132
	v_rcp_f32_e32 v133, v133
	s_nop 0
	v_fmac_f32_e32 v134, v70, v130
	v_fmac_f32_e32 v135, v71, v131
	v_fmac_f32_e32 v136, v72, v132
	v_fmac_f32_e32 v137, v73, v133
	v_cvt_pk_bf16_f32 v70, v134, v135
	v_cvt_pk_bf16_f32 v71, v136, v137
	v_lshlrev_b32_e32 v130, 16, v220
	v_and_b32_e32 v131, 0xffff0000, v220
	v_lshlrev_b32_e32 v132, 16, v221
	v_and_b32_e32 v133, 0xffff0000, v221
	v_mul_f32_e32 v130, 0xbfb8aa3b, v130
	v_mul_f32_e32 v131, 0xbfb8aa3b, v131
	v_mul_f32_e32 v132, 0xbfb8aa3b, v132
	v_mul_f32_e32 v133, 0xbfb8aa3b, v133
	v_exp_f32_e32 v130, v130
	v_exp_f32_e32 v131, v131
	v_exp_f32_e32 v132, v132
	v_exp_f32_e32 v133, v133
	v_lshlrev_b32_e32 v134, 16, v224
	v_and_b32_e32 v135, 0xffff0000, v224
	v_lshlrev_b32_e32 v136, 16, v225
	v_and_b32_e32 v137, 0xffff0000, v225
	v_add_f32_e32 v130, 1.0, v130
	v_add_f32_e32 v131, 1.0, v131
	v_add_f32_e32 v132, 1.0, v132
	v_add_f32_e32 v133, 1.0, v133
	v_rcp_f32_e32 v130, v130
	v_rcp_f32_e32 v131, v131
	v_rcp_f32_e32 v132, v132
	v_rcp_f32_e32 v133, v133
	s_nop 0
	v_fmac_f32_e32 v134, v66, v130
	v_fmac_f32_e32 v135, v67, v131
	v_fmac_f32_e32 v136, v68, v132
	v_fmac_f32_e32 v137, v69, v133
	v_cvt_pk_bf16_f32 v72, v134, v135
	v_cvt_pk_bf16_f32 v73, v136, v137
	global_load_dwordx4 v[210:213], v[138:139], off
	global_load_dwordx4 v[218:221], v[138:139], off offset:256
	v_lshl_add_u64 v[138:139], v[138:139], 0, s[0:1]
	v_lshl_add_u64 v[140:141], v[140:141], 0, s[34:35]
	global_store_dwordx4 v[142:143], v[78:81], off
	global_store_dwordx4 v[142:143], v[70:73], off offset:256
	v_lshl_add_u64 v[142:143], v[142:143], 0, s[38:39]
	s_waitcnt vmcnt(10)
	v_mov_b32_e32 v230, 0
	v_mov_b32_e32 v231, 0
	v_mov_b32_e32 v232, 0
	v_mov_b32_e32 v233, 0
	v_lshlrev_b32_e32 v130, 16, v226
	v_and_b32_e32 v131, 0xffff0000, v226
	v_lshlrev_b32_e32 v132, 16, v227
	v_and_b32_e32 v133, 0xffff0000, v227
	v_mul_f32_e32 v130, 0xbfb8aa3b, v130
	v_mul_f32_e32 v131, 0xbfb8aa3b, v131
	v_mul_f32_e32 v132, 0xbfb8aa3b, v132
	v_mul_f32_e32 v133, 0xbfb8aa3b, v133
	v_exp_f32_e32 v130, v130
	v_exp_f32_e32 v131, v131
	v_exp_f32_e32 v132, v132
	v_exp_f32_e32 v133, v133
	v_lshlrev_b32_e32 v134, 16, v230
	v_and_b32_e32 v135, 0xffff0000, v230
	v_lshlrev_b32_e32 v136, 16, v231
	v_and_b32_e32 v137, 0xffff0000, v231
	v_add_f32_e32 v130, 1.0, v130
	v_add_f32_e32 v131, 1.0, v131
	v_add_f32_e32 v132, 1.0, v132
	v_add_f32_e32 v133, 1.0, v133
	v_rcp_f32_e32 v130, v130
	v_rcp_f32_e32 v131, v131
	v_rcp_f32_e32 v132, v132
	v_rcp_f32_e32 v133, v133
	s_nop 0
	v_fmac_f32_e32 v134, v62, v130
	v_fmac_f32_e32 v135, v63, v131
	v_fmac_f32_e32 v136, v64, v132
	v_fmac_f32_e32 v137, v65, v133
	v_cvt_pk_bf16_f32 v62, v134, v135
	v_cvt_pk_bf16_f32 v63, v136, v137
	v_lshlrev_b32_e32 v130, 16, v228
	v_and_b32_e32 v131, 0xffff0000, v228
	v_lshlrev_b32_e32 v132, 16, v229
	v_and_b32_e32 v133, 0xffff0000, v229
	v_mul_f32_e32 v130, 0xbfb8aa3b, v130
	v_mul_f32_e32 v131, 0xbfb8aa3b, v131
	v_mul_f32_e32 v132, 0xbfb8aa3b, v132
	v_mul_f32_e32 v133, 0xbfb8aa3b, v133
	v_exp_f32_e32 v130, v130
	v_exp_f32_e32 v131, v131
	v_exp_f32_e32 v132, v132
	v_exp_f32_e32 v133, v133
	v_lshlrev_b32_e32 v134, 16, v232
	v_and_b32_e32 v135, 0xffff0000, v232
	v_lshlrev_b32_e32 v136, 16, v233
	v_and_b32_e32 v137, 0xffff0000, v233
	v_add_f32_e32 v130, 1.0, v130
	v_add_f32_e32 v131, 1.0, v131
	v_add_f32_e32 v132, 1.0, v132
	v_add_f32_e32 v133, 1.0, v133
	v_rcp_f32_e32 v130, v130
	v_rcp_f32_e32 v131, v131
	v_rcp_f32_e32 v132, v132
	v_rcp_f32_e32 v133, v133
	s_nop 0
	v_fmac_f32_e32 v134, v58, v130
	v_fmac_f32_e32 v135, v59, v131
	v_fmac_f32_e32 v136, v60, v132
	v_fmac_f32_e32 v137, v61, v133
	v_cvt_pk_bf16_f32 v64, v134, v135
	v_cvt_pk_bf16_f32 v65, v136, v137
	v_mov_b32_e32 v238, 0
	v_mov_b32_e32 v239, 0
	v_mov_b32_e32 v240, 0
	v_mov_b32_e32 v241, 0
	v_lshlrev_b32_e32 v130, 16, v234
	v_and_b32_e32 v131, 0xffff0000, v234
	v_lshlrev_b32_e32 v132, 16, v235
	v_and_b32_e32 v133, 0xffff0000, v235
	v_mul_f32_e32 v130, 0xbfb8aa3b, v130
	v_mul_f32_e32 v131, 0xbfb8aa3b, v131
	v_mul_f32_e32 v132, 0xbfb8aa3b, v132
	v_mul_f32_e32 v133, 0xbfb8aa3b, v133
	v_exp_f32_e32 v130, v130
	v_exp_f32_e32 v131, v131
	v_exp_f32_e32 v132, v132
	v_exp_f32_e32 v133, v133
	v_lshlrev_b32_e32 v134, 16, v238
	v_and_b32_e32 v135, 0xffff0000, v238
	v_lshlrev_b32_e32 v136, 16, v239
	v_and_b32_e32 v137, 0xffff0000, v239
	v_add_f32_e32 v130, 1.0, v130
	v_add_f32_e32 v131, 1.0, v131
	v_add_f32_e32 v132, 1.0, v132
	v_add_f32_e32 v133, 1.0, v133
	v_rcp_f32_e32 v130, v130
	v_rcp_f32_e32 v131, v131
	v_rcp_f32_e32 v132, v132
	v_rcp_f32_e32 v133, v133
	s_nop 0
	v_fmac_f32_e32 v134, v54, v130
	v_fmac_f32_e32 v135, v55, v131
	v_fmac_f32_e32 v136, v56, v132
	v_fmac_f32_e32 v137, v57, v133
	v_cvt_pk_bf16_f32 v54, v134, v135
	v_cvt_pk_bf16_f32 v55, v136, v137
	v_lshlrev_b32_e32 v130, 16, v236
	v_and_b32_e32 v131, 0xffff0000, v236
	v_lshlrev_b32_e32 v132, 16, v237
	v_and_b32_e32 v133, 0xffff0000, v237
	v_mul_f32_e32 v130, 0xbfb8aa3b, v130
	v_mul_f32_e32 v131, 0xbfb8aa3b, v131
	v_mul_f32_e32 v132, 0xbfb8aa3b, v132
	v_mul_f32_e32 v133, 0xbfb8aa3b, v133
	v_exp_f32_e32 v130, v130
	v_exp_f32_e32 v131, v131
	v_exp_f32_e32 v132, v132
	v_exp_f32_e32 v133, v133
	v_lshlrev_b32_e32 v134, 16, v240
	v_and_b32_e32 v135, 0xffff0000, v240
	v_lshlrev_b32_e32 v136, 16, v241
	v_and_b32_e32 v137, 0xffff0000, v241
	v_add_f32_e32 v130, 1.0, v130
	v_add_f32_e32 v131, 1.0, v131
	v_add_f32_e32 v132, 1.0, v132
	v_add_f32_e32 v133, 1.0, v133
	v_rcp_f32_e32 v130, v130
	v_rcp_f32_e32 v131, v131
	v_rcp_f32_e32 v132, v132
	v_rcp_f32_e32 v133, v133
	s_nop 0
	v_fmac_f32_e32 v134, v50, v130
	v_fmac_f32_e32 v135, v51, v131
	v_fmac_f32_e32 v136, v52, v132
	v_fmac_f32_e32 v137, v53, v133
	v_cvt_pk_bf16_f32 v56, v134, v135
	v_cvt_pk_bf16_f32 v57, v136, v137
	global_load_dwordx4 v[226:229], v[138:139], off
	global_load_dwordx4 v[234:237], v[138:139], off offset:256
	global_store_dwordx4 v[142:143], v[62:65], off
	global_store_dwordx4 v[142:143], v[54:57], off offset:256
	v_lshl_add_u64 v[142:143], v[142:143], 0, s[34:35]
	s_waitcnt vmcnt(10)
	v_mov_b32_e32 v186, 0
	v_mov_b32_e32 v187, 0
	v_mov_b32_e32 v188, 0
	v_mov_b32_e32 v189, 0
	v_lshlrev_b32_e32 v130, 16, v182
	v_and_b32_e32 v131, 0xffff0000, v182
	v_lshlrev_b32_e32 v132, 16, v183
	v_and_b32_e32 v133, 0xffff0000, v183
	v_mul_f32_e32 v130, 0xbfb8aa3b, v130
	v_mul_f32_e32 v131, 0xbfb8aa3b, v131
	v_mul_f32_e32 v132, 0xbfb8aa3b, v132
	v_mul_f32_e32 v133, 0xbfb8aa3b, v133
	v_exp_f32_e32 v130, v130
	v_exp_f32_e32 v131, v131
	v_exp_f32_e32 v132, v132
	v_exp_f32_e32 v133, v133
	v_lshlrev_b32_e32 v134, 16, v186
	v_and_b32_e32 v135, 0xffff0000, v186
	v_lshlrev_b32_e32 v136, 16, v187
	v_and_b32_e32 v137, 0xffff0000, v187
	v_add_f32_e32 v130, 1.0, v130
	v_add_f32_e32 v131, 1.0, v131
	v_add_f32_e32 v132, 1.0, v132
	v_add_f32_e32 v133, 1.0, v133
	v_rcp_f32_e32 v130, v130
	v_rcp_f32_e32 v131, v131
	v_rcp_f32_e32 v132, v132
	v_rcp_f32_e32 v133, v133
	s_nop 0
	v_fmac_f32_e32 v134, v46, v130
	v_fmac_f32_e32 v135, v47, v131
	v_fmac_f32_e32 v136, v48, v132
	v_fmac_f32_e32 v137, v49, v133
	v_cvt_pk_bf16_f32 v46, v134, v135
	v_cvt_pk_bf16_f32 v47, v136, v137
	v_lshlrev_b32_e32 v130, 16, v184
	v_and_b32_e32 v131, 0xffff0000, v184
	v_lshlrev_b32_e32 v132, 16, v185
	v_and_b32_e32 v133, 0xffff0000, v185
	v_mul_f32_e32 v130, 0xbfb8aa3b, v130
	v_mul_f32_e32 v131, 0xbfb8aa3b, v131
	v_mul_f32_e32 v132, 0xbfb8aa3b, v132
	v_mul_f32_e32 v133, 0xbfb8aa3b, v133
	v_exp_f32_e32 v130, v130
	v_exp_f32_e32 v131, v131
	v_exp_f32_e32 v132, v132
	v_exp_f32_e32 v133, v133
	v_lshlrev_b32_e32 v134, 16, v188
	v_and_b32_e32 v135, 0xffff0000, v188
	v_lshlrev_b32_e32 v136, 16, v189
	v_and_b32_e32 v137, 0xffff0000, v189
	v_add_f32_e32 v130, 1.0, v130
	v_add_f32_e32 v131, 1.0, v131
	v_add_f32_e32 v132, 1.0, v132
	v_add_f32_e32 v133, 1.0, v133
	v_rcp_f32_e32 v130, v130
	v_rcp_f32_e32 v131, v131
	v_rcp_f32_e32 v132, v132
	v_rcp_f32_e32 v133, v133
	s_nop 0
	v_fmac_f32_e32 v134, v42, v130
	v_fmac_f32_e32 v135, v43, v131
	v_fmac_f32_e32 v136, v44, v132
	v_fmac_f32_e32 v137, v45, v133
	v_cvt_pk_bf16_f32 v48, v134, v135
	v_cvt_pk_bf16_f32 v49, v136, v137
	v_mov_b32_e32 v242, 0
	v_mov_b32_e32 v243, 0
	v_mov_b32_e32 v244, 0
	v_mov_b32_e32 v245, 0
	v_lshlrev_b32_e32 v130, 16, v190
	v_and_b32_e32 v131, 0xffff0000, v190
	v_lshlrev_b32_e32 v132, 16, v191
	v_and_b32_e32 v133, 0xffff0000, v191
	v_mul_f32_e32 v130, 0xbfb8aa3b, v130
	v_mul_f32_e32 v131, 0xbfb8aa3b, v131
	v_mul_f32_e32 v132, 0xbfb8aa3b, v132
	v_mul_f32_e32 v133, 0xbfb8aa3b, v133
	v_exp_f32_e32 v130, v130
	v_exp_f32_e32 v131, v131
	v_exp_f32_e32 v132, v132
	v_exp_f32_e32 v133, v133
	v_lshlrev_b32_e32 v134, 16, v242
	v_and_b32_e32 v135, 0xffff0000, v242
	v_lshlrev_b32_e32 v136, 16, v243
	v_and_b32_e32 v137, 0xffff0000, v243
	v_add_f32_e32 v130, 1.0, v130
	v_add_f32_e32 v131, 1.0, v131
	v_add_f32_e32 v132, 1.0, v132
	v_add_f32_e32 v133, 1.0, v133
	v_rcp_f32_e32 v130, v130
	v_rcp_f32_e32 v131, v131
	v_rcp_f32_e32 v132, v132
	v_rcp_f32_e32 v133, v133
	s_nop 0
	v_fmac_f32_e32 v134, v38, v130
	v_fmac_f32_e32 v135, v39, v131
	v_fmac_f32_e32 v136, v40, v132
	v_fmac_f32_e32 v137, v41, v133
	v_cvt_pk_bf16_f32 v38, v134, v135
	v_cvt_pk_bf16_f32 v39, v136, v137
	v_lshlrev_b32_e32 v130, 16, v192
	v_and_b32_e32 v131, 0xffff0000, v192
	v_lshlrev_b32_e32 v132, 16, v193
	v_and_b32_e32 v133, 0xffff0000, v193
	v_mul_f32_e32 v130, 0xbfb8aa3b, v130
	v_mul_f32_e32 v131, 0xbfb8aa3b, v131
	v_mul_f32_e32 v132, 0xbfb8aa3b, v132
	v_mul_f32_e32 v133, 0xbfb8aa3b, v133
	v_exp_f32_e32 v130, v130
	v_exp_f32_e32 v131, v131
	v_exp_f32_e32 v132, v132
	v_exp_f32_e32 v133, v133
	v_lshlrev_b32_e32 v134, 16, v244
	v_and_b32_e32 v135, 0xffff0000, v244
	v_lshlrev_b32_e32 v136, 16, v245
	v_and_b32_e32 v137, 0xffff0000, v245
	v_add_f32_e32 v130, 1.0, v130
	v_add_f32_e32 v131, 1.0, v131
	v_add_f32_e32 v132, 1.0, v132
	v_add_f32_e32 v133, 1.0, v133
	v_rcp_f32_e32 v130, v130
	v_rcp_f32_e32 v131, v131
	v_rcp_f32_e32 v132, v132
	v_rcp_f32_e32 v133, v133
	s_nop 0
	v_fmac_f32_e32 v134, v34, v130
	v_fmac_f32_e32 v135, v35, v131
	v_fmac_f32_e32 v136, v36, v132
	v_fmac_f32_e32 v137, v37, v133
	v_cvt_pk_bf16_f32 v40, v134, v135
	v_cvt_pk_bf16_f32 v41, v136, v137
	global_store_dwordx4 v[142:143], v[46:49], off
	global_store_dwordx4 v[142:143], v[38:41], off offset:256
	v_lshl_add_u64 v[142:143], v[142:143], 0, s[34:35]
	s_waitcnt vmcnt(8)
	v_mov_b32_e32 v214, 0
	v_mov_b32_e32 v215, 0
	v_mov_b32_e32 v216, 0
	v_mov_b32_e32 v217, 0
	v_lshlrev_b32_e32 v130, 16, v210
	v_and_b32_e32 v131, 0xffff0000, v210
	v_lshlrev_b32_e32 v132, 16, v211
	v_and_b32_e32 v133, 0xffff0000, v211
	v_mul_f32_e32 v130, 0xbfb8aa3b, v130
	v_mul_f32_e32 v131, 0xbfb8aa3b, v131
	v_mul_f32_e32 v132, 0xbfb8aa3b, v132
	v_mul_f32_e32 v133, 0xbfb8aa3b, v133
	v_exp_f32_e32 v130, v130
	v_exp_f32_e32 v131, v131
	v_exp_f32_e32 v132, v132
	v_exp_f32_e32 v133, v133
	v_lshlrev_b32_e32 v134, 16, v214
	v_and_b32_e32 v135, 0xffff0000, v214
	v_lshlrev_b32_e32 v136, 16, v215
	v_and_b32_e32 v137, 0xffff0000, v215
	v_add_f32_e32 v130, 1.0, v130
	v_add_f32_e32 v131, 1.0, v131
	v_add_f32_e32 v132, 1.0, v132
	v_add_f32_e32 v133, 1.0, v133
	v_rcp_f32_e32 v130, v130
	v_rcp_f32_e32 v131, v131
	v_rcp_f32_e32 v132, v132
	v_rcp_f32_e32 v133, v133
	s_nop 0
	v_fmac_f32_e32 v134, v30, v130
	v_fmac_f32_e32 v135, v31, v131
	v_fmac_f32_e32 v136, v32, v132
	v_fmac_f32_e32 v137, v33, v133
	v_cvt_pk_bf16_f32 v30, v134, v135
	v_cvt_pk_bf16_f32 v31, v136, v137
	v_lshlrev_b32_e32 v130, 16, v212
	v_and_b32_e32 v131, 0xffff0000, v212
	v_lshlrev_b32_e32 v132, 16, v213
	v_and_b32_e32 v133, 0xffff0000, v213
	v_mul_f32_e32 v130, 0xbfb8aa3b, v130
	v_mul_f32_e32 v131, 0xbfb8aa3b, v131
	v_mul_f32_e32 v132, 0xbfb8aa3b, v132
	v_mul_f32_e32 v133, 0xbfb8aa3b, v133
	v_exp_f32_e32 v130, v130
	v_exp_f32_e32 v131, v131
	v_exp_f32_e32 v132, v132
	v_exp_f32_e32 v133, v133
	v_lshlrev_b32_e32 v134, 16, v216
	v_and_b32_e32 v135, 0xffff0000, v216
	v_lshlrev_b32_e32 v136, 16, v217
	v_and_b32_e32 v137, 0xffff0000, v217
	v_add_f32_e32 v130, 1.0, v130
	v_add_f32_e32 v131, 1.0, v131
	v_add_f32_e32 v132, 1.0, v132
	v_add_f32_e32 v133, 1.0, v133
	v_rcp_f32_e32 v130, v130
	v_rcp_f32_e32 v131, v131
	v_rcp_f32_e32 v132, v132
	v_rcp_f32_e32 v133, v133
	s_nop 0
	v_fmac_f32_e32 v134, v26, v130
	v_fmac_f32_e32 v135, v27, v131
	v_fmac_f32_e32 v136, v28, v132
	v_fmac_f32_e32 v137, v29, v133
	v_cvt_pk_bf16_f32 v32, v134, v135
	v_cvt_pk_bf16_f32 v33, v136, v137
	v_mov_b32_e32 v222, 0
	v_mov_b32_e32 v223, 0
	v_mov_b32_e32 v224, 0
	v_mov_b32_e32 v225, 0
	v_lshlrev_b32_e32 v130, 16, v218
	v_and_b32_e32 v131, 0xffff0000, v218
	v_lshlrev_b32_e32 v132, 16, v219
	v_and_b32_e32 v133, 0xffff0000, v219
	v_mul_f32_e32 v130, 0xbfb8aa3b, v130
	v_mul_f32_e32 v131, 0xbfb8aa3b, v131
	v_mul_f32_e32 v132, 0xbfb8aa3b, v132
	v_mul_f32_e32 v133, 0xbfb8aa3b, v133
	v_exp_f32_e32 v130, v130
	v_exp_f32_e32 v131, v131
	v_exp_f32_e32 v132, v132
	v_exp_f32_e32 v133, v133
	v_lshlrev_b32_e32 v134, 16, v222
	v_and_b32_e32 v135, 0xffff0000, v222
	v_lshlrev_b32_e32 v136, 16, v223
	v_and_b32_e32 v137, 0xffff0000, v223
	v_add_f32_e32 v130, 1.0, v130
	v_add_f32_e32 v131, 1.0, v131
	v_add_f32_e32 v132, 1.0, v132
	v_add_f32_e32 v133, 1.0, v133
	v_rcp_f32_e32 v130, v130
	v_rcp_f32_e32 v131, v131
	v_rcp_f32_e32 v132, v132
	v_rcp_f32_e32 v133, v133
	s_nop 0
	v_fmac_f32_e32 v134, v22, v130
	v_fmac_f32_e32 v135, v23, v131
	v_fmac_f32_e32 v136, v24, v132
	v_fmac_f32_e32 v137, v25, v133
	v_cvt_pk_bf16_f32 v22, v134, v135
	v_cvt_pk_bf16_f32 v23, v136, v137
	v_lshlrev_b32_e32 v130, 16, v220
	v_and_b32_e32 v131, 0xffff0000, v220
	v_lshlrev_b32_e32 v132, 16, v221
	v_and_b32_e32 v133, 0xffff0000, v221
	v_mul_f32_e32 v130, 0xbfb8aa3b, v130
	v_mul_f32_e32 v131, 0xbfb8aa3b, v131
	v_mul_f32_e32 v132, 0xbfb8aa3b, v132
	v_mul_f32_e32 v133, 0xbfb8aa3b, v133
	v_exp_f32_e32 v130, v130
	v_exp_f32_e32 v131, v131
	v_exp_f32_e32 v132, v132
	v_exp_f32_e32 v133, v133
	v_lshlrev_b32_e32 v134, 16, v224
	v_and_b32_e32 v135, 0xffff0000, v224
	v_lshlrev_b32_e32 v136, 16, v225
	v_and_b32_e32 v137, 0xffff0000, v225
	v_add_f32_e32 v130, 1.0, v130
	v_add_f32_e32 v131, 1.0, v131
	v_add_f32_e32 v132, 1.0, v132
	v_add_f32_e32 v133, 1.0, v133
	v_rcp_f32_e32 v130, v130
	v_rcp_f32_e32 v131, v131
	v_rcp_f32_e32 v132, v132
	v_rcp_f32_e32 v133, v133
	s_nop 0
	v_fmac_f32_e32 v134, v18, v130
	v_fmac_f32_e32 v135, v19, v131
	v_fmac_f32_e32 v136, v20, v132
	v_fmac_f32_e32 v137, v21, v133
	v_cvt_pk_bf16_f32 v24, v134, v135
	v_cvt_pk_bf16_f32 v25, v136, v137
	global_store_dwordx4 v[142:143], v[30:33], off
	global_store_dwordx4 v[142:143], v[22:25], off offset:256
	v_lshl_add_u64 v[142:143], v[142:143], 0, s[34:35]
	s_waitcnt vmcnt(6)
	v_mov_b32_e32 v230, 0
	v_mov_b32_e32 v231, 0
	v_mov_b32_e32 v232, 0
	v_mov_b32_e32 v233, 0
	v_lshlrev_b32_e32 v130, 16, v226
	v_and_b32_e32 v131, 0xffff0000, v226
	v_lshlrev_b32_e32 v132, 16, v227
	v_and_b32_e32 v133, 0xffff0000, v227
	v_mul_f32_e32 v130, 0xbfb8aa3b, v130
	v_mul_f32_e32 v131, 0xbfb8aa3b, v131
	v_mul_f32_e32 v132, 0xbfb8aa3b, v132
	v_mul_f32_e32 v133, 0xbfb8aa3b, v133
	v_exp_f32_e32 v130, v130
	v_exp_f32_e32 v131, v131
	v_exp_f32_e32 v132, v132
	v_exp_f32_e32 v133, v133
	v_lshlrev_b32_e32 v134, 16, v230
	v_and_b32_e32 v135, 0xffff0000, v230
	v_lshlrev_b32_e32 v136, 16, v231
	v_and_b32_e32 v137, 0xffff0000, v231
	v_add_f32_e32 v130, 1.0, v130
	v_add_f32_e32 v131, 1.0, v131
	v_add_f32_e32 v132, 1.0, v132
	v_add_f32_e32 v133, 1.0, v133
	v_rcp_f32_e32 v130, v130
	v_rcp_f32_e32 v131, v131
	v_rcp_f32_e32 v132, v132
	v_rcp_f32_e32 v133, v133
	s_nop 0
	v_fmac_f32_e32 v134, v14, v130
	v_fmac_f32_e32 v135, v15, v131
	v_fmac_f32_e32 v136, v16, v132
	v_fmac_f32_e32 v137, v17, v133
	v_cvt_pk_bf16_f32 v14, v134, v135
	v_cvt_pk_bf16_f32 v15, v136, v137
	v_lshlrev_b32_e32 v130, 16, v228
	v_and_b32_e32 v131, 0xffff0000, v228
	v_lshlrev_b32_e32 v132, 16, v229
	v_and_b32_e32 v133, 0xffff0000, v229
	v_mul_f32_e32 v130, 0xbfb8aa3b, v130
	v_mul_f32_e32 v131, 0xbfb8aa3b, v131
	v_mul_f32_e32 v132, 0xbfb8aa3b, v132
	v_mul_f32_e32 v133, 0xbfb8aa3b, v133
	v_exp_f32_e32 v130, v130
	v_exp_f32_e32 v131, v131
	v_exp_f32_e32 v132, v132
	v_exp_f32_e32 v133, v133
	v_lshlrev_b32_e32 v134, 16, v232
	v_and_b32_e32 v135, 0xffff0000, v232
	v_lshlrev_b32_e32 v136, 16, v233
	v_and_b32_e32 v137, 0xffff0000, v233
	v_add_f32_e32 v130, 1.0, v130
	v_add_f32_e32 v131, 1.0, v131
	v_add_f32_e32 v132, 1.0, v132
	v_add_f32_e32 v133, 1.0, v133
	v_rcp_f32_e32 v130, v130
	v_rcp_f32_e32 v131, v131
	v_rcp_f32_e32 v132, v132
	v_rcp_f32_e32 v133, v133
	s_nop 0
	v_fmac_f32_e32 v134, v10, v130
	v_fmac_f32_e32 v135, v11, v131
	v_fmac_f32_e32 v136, v12, v132
	v_fmac_f32_e32 v137, v13, v133
	v_cvt_pk_bf16_f32 v16, v134, v135
	v_cvt_pk_bf16_f32 v17, v136, v137
	v_mov_b32_e32 v238, 0
	v_mov_b32_e32 v239, 0
	v_mov_b32_e32 v240, 0
	v_mov_b32_e32 v241, 0
	v_lshlrev_b32_e32 v130, 16, v234
	v_and_b32_e32 v131, 0xffff0000, v234
	v_lshlrev_b32_e32 v132, 16, v235
	v_and_b32_e32 v133, 0xffff0000, v235
	v_mul_f32_e32 v130, 0xbfb8aa3b, v130
	v_mul_f32_e32 v131, 0xbfb8aa3b, v131
	v_mul_f32_e32 v132, 0xbfb8aa3b, v132
	v_mul_f32_e32 v133, 0xbfb8aa3b, v133
	v_exp_f32_e32 v130, v130
	v_exp_f32_e32 v131, v131
	v_exp_f32_e32 v132, v132
	v_exp_f32_e32 v133, v133
	v_lshlrev_b32_e32 v134, 16, v238
	v_and_b32_e32 v135, 0xffff0000, v238
	v_lshlrev_b32_e32 v136, 16, v239
	v_and_b32_e32 v137, 0xffff0000, v239
	v_add_f32_e32 v130, 1.0, v130
	v_add_f32_e32 v131, 1.0, v131
	v_add_f32_e32 v132, 1.0, v132
	v_add_f32_e32 v133, 1.0, v133
	v_rcp_f32_e32 v130, v130
	v_rcp_f32_e32 v131, v131
	v_rcp_f32_e32 v132, v132
	v_rcp_f32_e32 v133, v133
	s_nop 0
	v_fmac_f32_e32 v134, v6, v130
	v_fmac_f32_e32 v135, v7, v131
	v_fmac_f32_e32 v136, v8, v132
	v_fmac_f32_e32 v137, v9, v133
	v_cvt_pk_bf16_f32 v6, v134, v135
	v_cvt_pk_bf16_f32 v7, v136, v137
	v_lshlrev_b32_e32 v130, 16, v236
	v_and_b32_e32 v131, 0xffff0000, v236
	v_lshlrev_b32_e32 v132, 16, v237
	v_and_b32_e32 v133, 0xffff0000, v237
	v_mul_f32_e32 v130, 0xbfb8aa3b, v130
	v_mul_f32_e32 v131, 0xbfb8aa3b, v131
	v_mul_f32_e32 v132, 0xbfb8aa3b, v132
	v_mul_f32_e32 v133, 0xbfb8aa3b, v133
	v_exp_f32_e32 v130, v130
	v_exp_f32_e32 v131, v131
	v_exp_f32_e32 v132, v132
	v_exp_f32_e32 v133, v133
	v_lshlrev_b32_e32 v134, 16, v240
	v_and_b32_e32 v135, 0xffff0000, v240
	v_lshlrev_b32_e32 v136, 16, v241
	v_and_b32_e32 v137, 0xffff0000, v241
	v_add_f32_e32 v130, 1.0, v130
	v_add_f32_e32 v131, 1.0, v131
	v_add_f32_e32 v132, 1.0, v132
	v_add_f32_e32 v133, 1.0, v133
	v_rcp_f32_e32 v130, v130
	v_rcp_f32_e32 v131, v131
	v_rcp_f32_e32 v132, v132
	v_rcp_f32_e32 v133, v133
	s_nop 0
	v_fmac_f32_e32 v134, v2, v130
	v_fmac_f32_e32 v135, v3, v131
	v_fmac_f32_e32 v136, v4, v132
	v_fmac_f32_e32 v137, v5, v133
	v_cvt_pk_bf16_f32 v8, v134, v135
	v_cvt_pk_bf16_f32 v9, v136, v137
	global_store_dwordx4 v[142:143], v[14:17], off
	global_store_dwordx4 v[142:143], v[6:9], off offset:256
.Leg_fin:
	s_movk_i32 s8, 0xfa00
	s_mov_b32 s9, -1
	s_mov_b64 s[0:1], -1
	s_and_b64 vcc, exec, s[40:41]
	s_cbranch_vccnz .LBB0_194
	s_andn2_b64 vcc, exec, s[24:25]
	v_mov_b64 v[126:127], 0
	v_mov_b64 v[128:129], 0
	v_mov_b64 v[122:123], 0
	v_mov_b64 v[124:125], 0
	v_mov_b64 v[110:111], 0
	v_mov_b64 v[112:113], 0
	v_mov_b64 v[106:107], 0
	v_mov_b64 v[108:109], 0
	v_mov_b64 v[94:95], 0
	v_mov_b64 v[96:97], 0
	v_mov_b64 v[90:91], 0
	v_mov_b64 v[92:93], 0
	v_mov_b64 v[78:79], 0
	v_mov_b64 v[80:81], 0
	v_mov_b64 v[74:75], 0
	v_mov_b64 v[76:77], 0
	v_mov_b64 v[118:119], 0
	v_mov_b64 v[120:121], 0
	v_mov_b64 v[114:115], 0
	v_mov_b64 v[116:117], 0
	v_mov_b64 v[102:103], 0
	v_mov_b64 v[104:105], 0
	v_mov_b64 v[98:99], 0
	v_mov_b64 v[100:101], 0
	v_mov_b64 v[86:87], 0
	v_mov_b64 v[88:89], 0
	v_mov_b64 v[82:83], 0
	v_mov_b64 v[84:85], 0
	v_mov_b64 v[70:71], 0
	v_mov_b64 v[72:73], 0
	v_mov_b64 v[66:67], 0
	v_mov_b64 v[68:69], 0
	v_mov_b64 v[62:63], 0
	v_mov_b64 v[64:65], 0
	v_mov_b64 v[58:59], 0
	v_mov_b64 v[60:61], 0
	v_mov_b64 v[46:47], 0
	v_mov_b64 v[48:49], 0
	v_mov_b64 v[42:43], 0
	v_mov_b64 v[44:45], 0
	v_mov_b64 v[30:31], 0
	v_mov_b64 v[32:33], 0
	v_mov_b64 v[26:27], 0
	v_mov_b64 v[28:29], 0
	v_mov_b64 v[14:15], 0
	v_mov_b64 v[16:17], 0
	v_mov_b64 v[10:11], 0
	v_mov_b64 v[12:13], 0
	v_mov_b64 v[54:55], 0
	v_mov_b64 v[56:57], 0
	v_mov_b64 v[50:51], 0
	v_mov_b64 v[52:53], 0
	v_mov_b64 v[38:39], 0
	v_mov_b64 v[40:41], 0
	v_mov_b64 v[34:35], 0
	v_mov_b64 v[36:37], 0
	v_mov_b64 v[22:23], 0
	v_mov_b64 v[24:25], 0
	v_mov_b64 v[18:19], 0
	v_mov_b64 v[20:21], 0
	v_mov_b64 v[6:7], 0
	v_mov_b64 v[8:9], 0
	v_mov_b64 v[2:3], 0
	v_mov_b64 v[4:5], 0
	s_cbranch_vccnz .LBB0_193
	s_barrier
	s_branch .LBB0_193
